# GLU epilogue value loads hoisted up front, per-row scale loads de-serialized in weight-convert loops, rotary cos and sin loads paired
# speedup vs baseline: 1.0118x; 1.0074x over previous
; __device__ __forceinline__ unsigned pack2(float lo, float hi) { const f32x2_t v = {lo, hi}; const bf16x2_t b = __builtin_convertvector(v, bf16x2_t); return __builtin_bit_cast(unsigned, b); }
; __device__ __forceinline__ float bflo(unsigned w) { return __uint_as_float(w << 16); }
; __device__ __forceinline__ float bfhi(unsigned w) { return __uint_as_float(w & 0xffff0000u); }
; __device__ __forceinline__ float fast_sigmoid(float x) { return __builtin_amdgcn_rcpf(1.0f + __expf(-x)); }
;     __device__ __forceinline__ void operator()(AccRef acc, const Unit& u, int wr, int wc, int fr, int fq, const LAS float* rsl) const {
;         const int row0 = u.pm * 256 + wr * 64 + fr, col0 = u.pn * 256 + wc * 32 + 8 * fq;
; #pragma unroll
;         for (int ai = 0; ai < 2; ++ai)
; #pragma unroll
;             for (int m = 0; m < 4; ++m) { const int r = row0 + ai * 128 + m * 16;
; #pragma unroll
;                 for (int bj = 0; bj < 2; ++bj) { const int c = col0 + bj * 128; const f32x4 v0 = acc[ai][bj][m][0], v1 = acc[ai][bj][m][1];
;                     const uint4 gy = *(const uint4*)(GY + (size_t)r * 512 + c); uint4 w;
;                     w.x = pack2(bflo(gy.x) * fast_sigmoid(v0[0]), bfhi(gy.x) * fast_sigmoid(v0[1])); w.y = pack2(bflo(gy.y) * fast_sigmoid(v0[2]), bfhi(gy.y) * fast_sigmoid(v0[3]));
;                     w.z = pack2(bflo(gy.z) * fast_sigmoid(v1[0]), bfhi(gy.z) * fast_sigmoid(v1[1])); w.w = pack2(bflo(gy.w) * fast_sigmoid(v1[2]), bfhi(gy.w) * fast_sigmoid(v1[3]));
;                     *(uint4*)(MIX + (size_t)r * 1024 + c) = w; } }
.LBB0_115:
	v_lshl_add_u32 v142, s20, 8, v144
	v_lshl_or_b32 v140, s10, 8, v146
	v_ashrrev_i32_e32 v143, 31, v142
	v_lshlrev_b64 v[148:149], 10, v[142:143]
	v_ashrrev_i32_e32 v141, 31, v140
	v_lshl_add_u64 v[148:149], s[34:35], 0, v[148:149]
	v_lshlrev_b64 v[140:141], 1, v[140:141]
	v_lshl_add_u64 v[154:155], v[148:149], 0, v[140:141]
	global_load_dwordx4 v[148:151], v[154:155], off
	v_lshl_add_u32 v182, v142, 10, v140
	global_load_dwordx4 v[158:161], v182, s[34:35] offset:256
	v_add_u32_e32 v183, 0x4000, v182
	global_load_dwordx4 v[162:165], v183, s[34:35]
	global_load_dwordx4 v[166:169], v183, s[34:35] offset:256
	v_add_u32_e32 v183, 0x8000, v182
	global_load_dwordx4 v[170:173], v183, s[34:35]
	global_load_dwordx4 v[174:177], v183, s[34:35] offset:256
	v_add_u32_e32 v183, 0xc000, v182
	global_load_dwordx4 v[178:181], v183, s[34:35]
	global_load_dwordx4 v[186:189], v183, s[34:35] offset:256
	v_add_u32_e32 v183, 0x20000, v182
	global_load_dwordx4 v[192:195], v183, s[34:35]
	global_load_dwordx4 v[202:205], v183, s[34:35] offset:256
	v_add_u32_e32 v183, 0x24000, v182
	global_load_dwordx4 v[206:209], v183, s[34:35]
	global_load_dwordx4 v[210:213], v183, s[34:35] offset:256
	v_add_u32_e32 v183, 0x28000, v182
	global_load_dwordx4 v[214:217], v183, s[34:35]
	global_load_dwordx4 v[218:221], v183, s[34:35] offset:256
	v_add_u32_e32 v183, 0x2c000, v182
	global_load_dwordx4 v[222:225], v183, s[34:35]
	v_mul_f32_e32 v124, 0xbfb8aa3b, v124
	v_mul_f32_e32 v125, 0xbfb8aa3b, v125
	v_exp_f32_e32 v124, v124
	v_exp_f32_e32 v125, v125
	v_mul_f32_e32 v120, 0xbfb8aa3b, v120
	v_mul_f32_e32 v121, 0xbfb8aa3b, v121
	v_add_f32_e32 v124, 1.0, v124
	v_add_f32_e32 v125, 1.0, v125
	v_rcp_f32_e32 v124, v124
	v_rcp_f32_e32 v125, v125
	v_exp_f32_e32 v120, v120
	v_exp_f32_e32 v121, v121
	v_mul_f32_e32 v123, 0xbfb8aa3b, v123
	v_exp_f32_e32 v123, v123
	v_add_f32_e32 v120, 1.0, v120
	v_add_f32_e32 v121, 1.0, v121
	v_rcp_f32_e32 v120, v120
	v_rcp_f32_e32 v121, v121
	v_add_f32_e32 v123, 1.0, v123
	v_rcp_f32_e32 v123, v123
	v_lshlrev_b64 v[152:153], 11, v[142:143]
	v_mul_f32_e32 v116, 0xbfb8aa3b, v116
	v_mul_f32_e32 v117, 0xbfb8aa3b, v117
	v_exp_f32_e32 v116, v116
	v_exp_f32_e32 v117, v117
	v_mul_f32_e32 v112, 0xbfb8aa3b, v112
	v_mul_f32_e32 v113, 0xbfb8aa3b, v113
	v_add_f32_e32 v116, 1.0, v116
	v_add_f32_e32 v117, 1.0, v117
	v_rcp_f32_e32 v116, v116
	v_rcp_f32_e32 v117, v117
	v_exp_f32_e32 v112, v112
	v_exp_f32_e32 v113, v113
	v_mul_f32_e32 v115, 0xbfb8aa3b, v115
	v_exp_f32_e32 v115, v115
	v_add_f32_e32 v112, 1.0, v112
	v_add_f32_e32 v113, 1.0, v113
	v_rcp_f32_e32 v112, v112
	v_rcp_f32_e32 v113, v113
	v_add_f32_e32 v115, 1.0, v115
	v_rcp_f32_e32 v115, v115
	v_mul_f32_e32 v108, 0xbfb8aa3b, v108
	v_mul_f32_e32 v109, 0xbfb8aa3b, v109
	v_exp_f32_e32 v108, v108
	v_exp_f32_e32 v109, v109
	v_mul_f32_e32 v104, 0xbfb8aa3b, v104
	v_mul_f32_e32 v105, 0xbfb8aa3b, v105
	v_add_f32_e32 v108, 1.0, v108
	v_add_f32_e32 v109, 1.0, v109
	v_rcp_f32_e32 v108, v108
	v_rcp_f32_e32 v109, v109
	v_exp_f32_e32 v104, v104
	v_exp_f32_e32 v105, v105
	v_mul_f32_e32 v107, 0xbfb8aa3b, v107
	v_exp_f32_e32 v107, v107
	v_add_f32_e32 v104, 1.0, v104
	v_add_f32_e32 v105, 1.0, v105
	v_rcp_f32_e32 v104, v104
	v_rcp_f32_e32 v105, v105
	v_add_f32_e32 v107, 1.0, v107
	v_rcp_f32_e32 v107, v107
	v_mul_f32_e32 v100, 0xbfb8aa3b, v100
	v_mul_f32_e32 v101, 0xbfb8aa3b, v101
	v_exp_f32_e32 v100, v100
	v_exp_f32_e32 v101, v101
	v_mul_f32_e32 v96, 0xbfb8aa3b, v96
	v_mul_f32_e32 v97, 0xbfb8aa3b, v97
	v_add_f32_e32 v100, 1.0, v100
	v_add_f32_e32 v101, 1.0, v101
	v_rcp_f32_e32 v100, v100
	v_rcp_f32_e32 v101, v101
	v_exp_f32_e32 v96, v96
	v_exp_f32_e32 v97, v97
	v_mul_f32_e32 v99, 0xbfb8aa3b, v99
	v_exp_f32_e32 v99, v99
	v_add_f32_e32 v96, 1.0, v96
	v_add_f32_e32 v97, 1.0, v97
	v_rcp_f32_e32 v96, v96
	v_rcp_f32_e32 v97, v97
	s_waitcnt vmcnt(14)
	v_lshlrev_b32_e32 v156, 16, v148
	v_and_b32_e32 v157, 0xffff0000, v148
	v_pk_mul_f32 v[124:125], v[124:125], v[156:157]
	v_lshlrev_b32_e32 v148, 16, v149
	v_cvt_pk_bf16_f32 v124, v124, v125
	v_mul_f32_e32 v125, 0xbfb8aa3b, v126
	v_exp_f32_e32 v125, v125
	v_and_b32_e32 v149, 0xffff0000, v149
	v_add_f32_e32 v99, 1.0, v99
	v_rcp_f32_e32 v99, v99
	v_add_f32_e32 v125, 1.0, v125
	v_rcp_f32_e32 v126, v125
	v_mul_f32_e32 v125, 0xbfb8aa3b, v127
	v_exp_f32_e32 v125, v125
	v_mul_f32_e32 v92, 0xbfb8aa3b, v92
	v_mul_f32_e32 v93, 0xbfb8aa3b, v93
	v_exp_f32_e32 v92, v92
	v_add_f32_e32 v125, 1.0, v125
	v_rcp_f32_e32 v127, v125
	v_exp_f32_e32 v93, v93
	v_add_f32_e32 v92, 1.0, v92
	v_rcp_f32_e32 v92, v92
	v_pk_mul_f32 v[126:127], v[126:127], v[148:149]
	v_add_f32_e32 v93, 1.0, v93
	v_cvt_pk_bf16_f32 v125, v126, v127
	v_lshlrev_b32_e32 v126, 16, v150
	v_and_b32_e32 v127, 0xffff0000, v150
	v_pk_mul_f32 v[120:121], v[120:121], v[126:127]
	v_rcp_f32_e32 v93, v93
	v_cvt_pk_bf16_f32 v126, v120, v121
	v_mul_f32_e32 v121, 0xbfb8aa3b, v122
	v_exp_f32_e32 v121, v121
	v_lshlrev_b32_e32 v120, 16, v151
	v_mul_f32_e32 v88, 0xbfb8aa3b, v88
	v_mul_f32_e32 v89, 0xbfb8aa3b, v89
	v_add_f32_e32 v121, 1.0, v121
	v_rcp_f32_e32 v122, v121
	v_and_b32_e32 v121, 0xffff0000, v151
	v_exp_f32_e32 v88, v88
	v_exp_f32_e32 v89, v89
	v_pk_mul_f32 v[120:121], v[122:123], v[120:121]
	v_mul_f32_e32 v91, 0xbfb8aa3b, v91
	v_cvt_pk_bf16_f32 v127, v120, v121
	v_lshl_add_u64 v[120:121], s[48:49], 0, v[152:153]
	v_lshl_add_u64 v[148:149], v[120:121], 0, v[140:141]
	v_add_f32_e32 v88, 1.0, v88
	global_store_dwordx4 v[148:149], v[124:127], off
	v_add_f32_e32 v89, 1.0, v89
	v_rcp_f32_e32 v88, v88
	v_rcp_f32_e32 v89, v89
	v_exp_f32_e32 v91, v91
	v_mul_f32_e32 v84, 0xbfb8aa3b, v84
	v_mul_f32_e32 v85, 0xbfb8aa3b, v85
	v_exp_f32_e32 v84, v84
; __device__ __forceinline__ unsigned pack2(float lo, float hi) { const f32x2_t v = {lo, hi}; const bf16x2_t b = __builtin_convertvector(v, bf16x2_t); return __builtin_bit_cast(unsigned, b); }
; __device__ __forceinline__ float bflo(unsigned w) { return __uint_as_float(w << 16); }
; __device__ __forceinline__ float bfhi(unsigned w) { return __uint_as_float(w & 0xffff0000u); }
; __device__ __forceinline__ float fast_sigmoid(float x) { return __builtin_amdgcn_rcpf(1.0f + __expf(-x)); }
;     __device__ __forceinline__ void operator()(AccRef acc, const Unit& u, int wr, int wc, int fr, int fq, const LAS float* rsl) const {
;     ...
;             for (int m = 0; m < 4; ++m) { const int r = row0 + ai * 128 + m * 16;
; #pragma unroll
;                 for (int bj = 0; bj < 2; ++bj) { const int c = col0 + bj * 128; const f32x4 v0 = acc[ai][bj][m][0], v1 = acc[ai][bj][m][1];
;                     const uint4 gy = *(const uint4*)(GY + (size_t)r * 512 + c); uint4 w;
;                     w.x = pack2(bflo(gy.x) * fast_sigmoid(v0[0]), bfhi(gy.x) * fast_sigmoid(v0[1])); w.y = pack2(bflo(gy.y) * fast_sigmoid(v0[2]), bfhi(gy.y) * fast_sigmoid(v0[3]));
;                     w.z = pack2(bflo(gy.z) * fast_sigmoid(v1[0]), bfhi(gy.z) * fast_sigmoid(v1[1])); w.w = pack2(bflo(gy.w) * fast_sigmoid(v1[2]), bfhi(gy.w) * fast_sigmoid(v1[3]));
;                     *(uint4*)(MIX + (size_t)r * 1024 + c) = w; } }
	v_add_f32_e32 v91, 1.0, v91
	v_rcp_f32_e32 v91, v91
	v_exp_f32_e32 v85, v85
	v_add_f32_e32 v84, 1.0, v84
	v_rcp_f32_e32 v84, v84
	v_mul_f32_e32 v80, 0xbfb8aa3b, v80
	v_add_f32_e32 v85, 1.0, v85
	v_rcp_f32_e32 v85, v85
	v_mul_f32_e32 v81, 0xbfb8aa3b, v81
	v_exp_f32_e32 v80, v80
	v_exp_f32_e32 v81, v81
	v_mul_f32_e32 v83, 0xbfb8aa3b, v83
	v_exp_f32_e32 v83, v83
	v_add_f32_e32 v80, 1.0, v80
	v_add_f32_e32 v81, 1.0, v81
	v_rcp_f32_e32 v80, v80
	v_rcp_f32_e32 v81, v81
	v_add_f32_e32 v83, 1.0, v83
	v_rcp_f32_e32 v83, v83
	v_mul_f32_e32 v76, 0xbfb8aa3b, v76
	v_mul_f32_e32 v77, 0xbfb8aa3b, v77
	v_exp_f32_e32 v76, v76
	v_exp_f32_e32 v77, v77
	v_mul_f32_e32 v72, 0xbfb8aa3b, v72
	v_mul_f32_e32 v73, 0xbfb8aa3b, v73
	v_add_f32_e32 v76, 1.0, v76
	v_add_f32_e32 v77, 1.0, v77
	v_rcp_f32_e32 v76, v76
	v_rcp_f32_e32 v77, v77
	v_exp_f32_e32 v72, v72
	v_exp_f32_e32 v73, v73
	v_mul_f32_e32 v75, 0xbfb8aa3b, v75
	v_exp_f32_e32 v75, v75
	v_add_f32_e32 v72, 1.0, v72
	v_add_f32_e32 v73, 1.0, v73
	v_rcp_f32_e32 v72, v72
	v_rcp_f32_e32 v73, v73
	v_add_f32_e32 v75, 1.0, v75
	v_rcp_f32_e32 v75, v75
	v_mul_f32_e32 v68, 0xbfb8aa3b, v68
	v_mul_f32_e32 v69, 0xbfb8aa3b, v69
	v_exp_f32_e32 v68, v68
	v_exp_f32_e32 v69, v69
	v_mul_f32_e32 v64, 0xbfb8aa3b, v64
	v_mul_f32_e32 v65, 0xbfb8aa3b, v65
	v_add_f32_e32 v68, 1.0, v68
	v_add_f32_e32 v69, 1.0, v69
	v_rcp_f32_e32 v68, v68
	v_rcp_f32_e32 v69, v69
	v_exp_f32_e32 v64, v64
	v_exp_f32_e32 v65, v65
	v_mul_f32_e32 v67, 0xbfb8aa3b, v67
	v_exp_f32_e32 v67, v67
	v_add_f32_e32 v64, 1.0, v64
	v_add_f32_e32 v65, 1.0, v65
	v_rcp_f32_e32 v64, v64
	v_rcp_f32_e32 v65, v65
	v_add_f32_e32 v67, 1.0, v67
	v_rcp_f32_e32 v67, v67
	v_mul_f32_e32 v60, 0xbfb8aa3b, v60
	v_mul_f32_e32 v61, 0xbfb8aa3b, v61
	v_exp_f32_e32 v60, v60
	v_exp_f32_e32 v61, v61
	v_mul_f32_e32 v56, 0xbfb8aa3b, v56
	v_mul_f32_e32 v57, 0xbfb8aa3b, v57
	v_add_f32_e32 v60, 1.0, v60
	v_add_f32_e32 v61, 1.0, v61
	v_rcp_f32_e32 v60, v60
	v_rcp_f32_e32 v61, v61
	v_exp_f32_e32 v56, v56
	s_waitcnt vmcnt(14)
	v_mov_b64_e32 v[120:121], v[158:159]
	v_mov_b64_e32 v[122:123], v[160:161]
	v_lshlrev_b32_e32 v124, 16, v120
	v_and_b32_e32 v125, 0xffff0000, v120
	v_pk_mul_f32 v[116:117], v[116:117], v[124:125]
	v_lshlrev_b32_e32 v120, 16, v121
	v_cvt_pk_bf16_f32 v116, v116, v117
	v_mul_f32_e32 v117, 0xbfb8aa3b, v118
	v_exp_f32_e32 v117, v117
	v_and_b32_e32 v121, 0xffff0000, v121
	v_exp_f32_e32 v57, v57
	v_add_f32_e32 v56, 1.0, v56
	v_add_f32_e32 v117, 1.0, v117
	v_rcp_f32_e32 v118, v117
	v_mul_f32_e32 v117, 0xbfb8aa3b, v119
	v_exp_f32_e32 v117, v117
	v_add_f32_e32 v57, 1.0, v57
	v_rcp_f32_e32 v56, v56
	v_rcp_f32_e32 v57, v57
	v_add_f32_e32 v117, 1.0, v117
	v_rcp_f32_e32 v119, v117
	v_mul_f32_e32 v59, 0xbfb8aa3b, v59
	v_exp_f32_e32 v59, v59
	v_mul_f32_e32 v52, 0xbfb8aa3b, v52
	v_pk_mul_f32 v[118:119], v[118:119], v[120:121]
	v_mul_f32_e32 v53, 0xbfb8aa3b, v53
	v_cvt_pk_bf16_f32 v117, v118, v119
	v_lshlrev_b32_e32 v118, 16, v122
	v_and_b32_e32 v119, 0xffff0000, v122
	v_pk_mul_f32 v[112:113], v[112:113], v[118:119]
	v_add_f32_e32 v59, 1.0, v59
	v_cvt_pk_bf16_f32 v118, v112, v113
	v_mul_f32_e32 v113, 0xbfb8aa3b, v114
	v_exp_f32_e32 v113, v113
	v_lshlrev_b32_e32 v112, 16, v123
	v_rcp_f32_e32 v59, v59
	v_exp_f32_e32 v52, v52
	v_add_f32_e32 v113, 1.0, v113
	v_rcp_f32_e32 v114, v113
	v_and_b32_e32 v113, 0xffff0000, v123
	v_exp_f32_e32 v53, v53
	v_add_f32_e32 v52, 1.0, v52
	v_pk_mul_f32 v[112:113], v[114:115], v[112:113]
	v_rcp_f32_e32 v52, v52
	v_cvt_pk_bf16_f32 v119, v112, v113
	v_or_b32_e32 v112, 16, v142
	v_ashrrev_i32_e32 v113, 31, v112
	v_lshlrev_b64 v[114:115], 10, v[112:113]
	global_store_dwordx4 v[148:149], v[116:119], off offset:256
	v_add_f32_e32 v53, 1.0, v53
	v_rcp_f32_e32 v53, v53
	v_lshlrev_b64 v[118:119], 11, v[112:113]
	v_lshl_add_u64 v[112:113], s[34:35], 0, v[114:115]
	v_lshl_add_u64 v[116:117], v[112:113], 0, v[140:141]
	v_mul_f32_e32 v48, 0xbfb8aa3b, v48
	v_mul_f32_e32 v49, 0xbfb8aa3b, v49
	v_exp_f32_e32 v48, v48
	v_exp_f32_e32 v49, v49
	v_mul_f32_e32 v51, 0xbfb8aa3b, v51
	v_exp_f32_e32 v51, v51
	v_add_f32_e32 v48, 1.0, v48
	v_add_f32_e32 v49, 1.0, v49
	v_rcp_f32_e32 v48, v48
	v_rcp_f32_e32 v49, v49
	v_add_f32_e32 v51, 1.0, v51
	v_rcp_f32_e32 v51, v51
	v_mul_f32_e32 v44, 0xbfb8aa3b, v44
	v_mul_f32_e32 v45, 0xbfb8aa3b, v45
	v_exp_f32_e32 v44, v44
	v_exp_f32_e32 v45, v45
	v_mul_f32_e32 v40, 0xbfb8aa3b, v40
	v_mul_f32_e32 v41, 0xbfb8aa3b, v41
	v_add_f32_e32 v44, 1.0, v44
	v_add_f32_e32 v45, 1.0, v45
	v_rcp_f32_e32 v44, v44
	v_rcp_f32_e32 v45, v45
	v_exp_f32_e32 v40, v40
	v_exp_f32_e32 v41, v41
	v_mul_f32_e32 v43, 0xbfb8aa3b, v43
	v_exp_f32_e32 v43, v43
	v_add_f32_e32 v40, 1.0, v40
	v_add_f32_e32 v41, 1.0, v41
	v_rcp_f32_e32 v40, v40
	v_rcp_f32_e32 v41, v41
	v_add_f32_e32 v43, 1.0, v43
	v_rcp_f32_e32 v43, v43
	v_mul_f32_e32 v36, 0xbfb8aa3b, v36
	v_mul_f32_e32 v37, 0xbfb8aa3b, v37
	v_exp_f32_e32 v36, v36
	v_exp_f32_e32 v37, v37
	v_mul_f32_e32 v32, 0xbfb8aa3b, v32
	v_mul_f32_e32 v33, 0xbfb8aa3b, v33
	v_add_f32_e32 v36, 1.0, v36
	v_add_f32_e32 v37, 1.0, v37
	v_rcp_f32_e32 v36, v36
	v_rcp_f32_e32 v37, v37
	v_exp_f32_e32 v32, v32
	v_exp_f32_e32 v33, v33
	v_mul_f32_e32 v35, 0xbfb8aa3b, v35
	v_exp_f32_e32 v35, v35
	v_add_f32_e32 v32, 1.0, v32
	v_add_f32_e32 v33, 1.0, v33
	v_rcp_f32_e32 v32, v32
	v_rcp_f32_e32 v33, v33
	v_add_f32_e32 v35, 1.0, v35
	v_rcp_f32_e32 v35, v35
	v_mul_f32_e32 v28, 0xbfb8aa3b, v28
	v_mul_f32_e32 v29, 0xbfb8aa3b, v29
	v_exp_f32_e32 v28, v28
	v_exp_f32_e32 v29, v29
	v_mul_f32_e32 v24, 0xbfb8aa3b, v24
	v_mul_f32_e32 v25, 0xbfb8aa3b, v25
	v_add_f32_e32 v28, 1.0, v28
	v_add_f32_e32 v29, 1.0, v29
	v_rcp_f32_e32 v28, v28
	v_rcp_f32_e32 v29, v29
	v_exp_f32_e32 v24, v24
	v_exp_f32_e32 v25, v25
	v_mul_f32_e32 v27, 0xbfb8aa3b, v27
	v_exp_f32_e32 v27, v27
	v_add_f32_e32 v24, 1.0, v24
	v_add_f32_e32 v25, 1.0, v25
	v_rcp_f32_e32 v24, v24
	v_rcp_f32_e32 v25, v25
	v_add_f32_e32 v27, 1.0, v27
	v_rcp_f32_e32 v27, v27
	v_mul_f32_e32 v20, 0xbfb8aa3b, v20
	v_mul_f32_e32 v21, 0xbfb8aa3b, v21
	v_exp_f32_e32 v20, v20
	v_exp_f32_e32 v21, v21
	v_mul_f32_e32 v16, 0xbfb8aa3b, v16
	v_mul_f32_e32 v17, 0xbfb8aa3b, v17
	v_add_f32_e32 v20, 1.0, v20
	s_waitcnt vmcnt(14)
; __device__ __forceinline__ unsigned pack2(float lo, float hi) { const f32x2_t v = {lo, hi}; const bf16x2_t b = __builtin_convertvector(v, bf16x2_t); return __builtin_bit_cast(unsigned, b); }
; __device__ __forceinline__ float bflo(unsigned w) { return __uint_as_float(w << 16); }
; __device__ __forceinline__ float bfhi(unsigned w) { return __uint_as_float(w & 0xffff0000u); }
; __device__ __forceinline__ float fast_sigmoid(float x) { return __builtin_amdgcn_rcpf(1.0f + __expf(-x)); }
;     __device__ __forceinline__ void operator()(AccRef acc, const Unit& u, int wr, int wc, int fr, int fq, const LAS float* rsl) const {
;     ...
;             for (int m = 0; m < 4; ++m) { const int r = row0 + ai * 128 + m * 16;
; #pragma unroll
;                 for (int bj = 0; bj < 2; ++bj) { const int c = col0 + bj * 128; const f32x4 v0 = acc[ai][bj][m][0], v1 = acc[ai][bj][m][1];
;                     const uint4 gy = *(const uint4*)(GY + (size_t)r * 512 + c); uint4 w;
;                     w.x = pack2(bflo(gy.x) * fast_sigmoid(v0[0]), bfhi(gy.x) * fast_sigmoid(v0[1])); w.y = pack2(bflo(gy.y) * fast_sigmoid(v0[2]), bfhi(gy.y) * fast_sigmoid(v0[3]));
;                     w.z = pack2(bflo(gy.z) * fast_sigmoid(v1[0]), bfhi(gy.z) * fast_sigmoid(v1[1])); w.w = pack2(bflo(gy.w) * fast_sigmoid(v1[2]), bfhi(gy.w) * fast_sigmoid(v1[3]));
;                     *(uint4*)(MIX + (size_t)r * 1024 + c) = w; } }
	v_mov_b64_e32 v[112:113], v[162:163]
	v_mov_b64_e32 v[114:115], v[164:165]
	v_lshlrev_b32_e32 v120, 16, v112
	v_and_b32_e32 v121, 0xffff0000, v112
	v_pk_mul_f32 v[108:109], v[108:109], v[120:121]
	v_lshlrev_b32_e32 v112, 16, v113
	v_cvt_pk_bf16_f32 v108, v108, v109
	v_mul_f32_e32 v109, 0xbfb8aa3b, v110
	v_exp_f32_e32 v109, v109
	v_and_b32_e32 v113, 0xffff0000, v113
	v_add_f32_e32 v21, 1.0, v21
	v_rcp_f32_e32 v20, v20
	v_add_f32_e32 v109, 1.0, v109
	v_rcp_f32_e32 v110, v109
	v_mul_f32_e32 v109, 0xbfb8aa3b, v111
	v_exp_f32_e32 v109, v109
	v_rcp_f32_e32 v21, v21
	v_exp_f32_e32 v16, v16
	v_exp_f32_e32 v17, v17
	v_add_f32_e32 v109, 1.0, v109
	v_rcp_f32_e32 v111, v109
	v_add_f32_e32 v16, 1.0, v16
	v_add_f32_e32 v17, 1.0, v17
	v_rcp_f32_e32 v16, v16
	v_pk_mul_f32 v[110:111], v[110:111], v[112:113]
	v_rcp_f32_e32 v17, v17
	v_cvt_pk_bf16_f32 v109, v110, v111
	v_lshlrev_b32_e32 v110, 16, v114
	v_and_b32_e32 v111, 0xffff0000, v114
	v_pk_mul_f32 v[104:105], v[104:105], v[110:111]
	v_mul_f32_e32 v19, 0xbfb8aa3b, v19
	v_cvt_pk_bf16_f32 v110, v104, v105
	v_mul_f32_e32 v105, 0xbfb8aa3b, v106
	v_exp_f32_e32 v105, v105
	v_lshlrev_b32_e32 v104, 16, v115
	v_exp_f32_e32 v19, v19
	v_mul_f32_e32 v12, 0xbfb8aa3b, v12
	v_add_f32_e32 v105, 1.0, v105
	v_rcp_f32_e32 v106, v105
	v_and_b32_e32 v105, 0xffff0000, v115
	v_add_f32_e32 v19, 1.0, v19
	v_rcp_f32_e32 v19, v19
	v_pk_mul_f32 v[104:105], v[106:107], v[104:105]
	v_mul_f32_e32 v13, 0xbfb8aa3b, v13
	v_cvt_pk_bf16_f32 v111, v104, v105
	v_lshl_add_u64 v[104:105], s[48:49], 0, v[118:119]
	v_lshl_add_u64 v[112:113], v[104:105], 0, v[140:141]
	v_exp_f32_e32 v12, v12
	global_store_dwordx4 v[112:113], v[108:111], off
	v_exp_f32_e32 v13, v13
	v_mul_f32_e32 v15, 0xbfb8aa3b, v15
	v_add_f32_e32 v12, 1.0, v12
	v_rcp_f32_e32 v12, v12
	v_add_f32_e32 v13, 1.0, v13
	v_rcp_f32_e32 v13, v13
	v_exp_f32_e32 v15, v15
	v_mul_f32_e32 v8, 0xbfb8aa3b, v8
	v_mul_f32_e32 v9, 0xbfb8aa3b, v9
	v_exp_f32_e32 v8, v8
	v_exp_f32_e32 v9, v9
	v_add_f32_e32 v15, 1.0, v15
	v_rcp_f32_e32 v15, v15
	v_add_f32_e32 v8, 1.0, v8
	v_add_f32_e32 v9, 1.0, v9
	v_rcp_f32_e32 v8, v8
	v_rcp_f32_e32 v9, v9
	v_mul_f32_e32 v11, 0xbfb8aa3b, v11
	v_exp_f32_e32 v11, v11
	v_mul_f32_e32 v4, 0xbfb8aa3b, v4
	v_mul_f32_e32 v5, 0xbfb8aa3b, v5
	v_exp_f32_e32 v4, v4
	v_add_f32_e32 v11, 1.0, v11
	v_rcp_f32_e32 v11, v11
	v_exp_f32_e32 v5, v5
	v_add_f32_e32 v4, 1.0, v4
	v_rcp_f32_e32 v4, v4
	v_mul_f32_e32 v0, 0xbfb8aa3b, v0
	v_add_f32_e32 v5, 1.0, v5
	v_rcp_f32_e32 v5, v5
	v_mul_f32_e32 v1, 0xbfb8aa3b, v1
	v_exp_f32_e32 v0, v0
	v_exp_f32_e32 v1, v1
	v_mul_f32_e32 v3, 0xbfb8aa3b, v3
	v_exp_f32_e32 v3, v3
	v_add_f32_e32 v0, 1.0, v0
	v_add_f32_e32 v1, 1.0, v1
	v_rcp_f32_e32 v0, v0
	v_rcp_f32_e32 v1, v1
	v_add_f32_e32 v3, 1.0, v3
	v_rcp_f32_e32 v3, v3
	s_mov_b64 s[20:21], -1
	s_andn2_b64 vcc, exec, s[40:41]
	v_mov_b32_e32 v232, v229
	v_mov_b32_e32 v233, v190
	s_waitcnt vmcnt(14)
	v_mov_b64_e32 v[104:105], v[166:167]
	v_mov_b64_e32 v[106:107], v[168:169]
	v_lshlrev_b32_e32 v108, 16, v104
	v_and_b32_e32 v109, 0xffff0000, v104
	v_pk_mul_f32 v[100:101], v[100:101], v[108:109]
	v_lshlrev_b32_e32 v104, 16, v105
	v_cvt_pk_bf16_f32 v100, v100, v101
	v_mul_f32_e32 v101, 0xbfb8aa3b, v102
	v_exp_f32_e32 v101, v101
	v_and_b32_e32 v105, 0xffff0000, v105
	v_add_f32_e32 v101, 1.0, v101
	v_rcp_f32_e32 v102, v101
	v_mul_f32_e32 v101, 0xbfb8aa3b, v103
	v_exp_f32_e32 v101, v101
	s_nop 0
	v_add_f32_e32 v101, 1.0, v101
	v_rcp_f32_e32 v103, v101
	s_nop 0
	v_pk_mul_f32 v[102:103], v[102:103], v[104:105]
	s_nop 0
	v_cvt_pk_bf16_f32 v101, v102, v103
	v_lshlrev_b32_e32 v102, 16, v106
	v_and_b32_e32 v103, 0xffff0000, v106
	v_pk_mul_f32 v[96:97], v[96:97], v[102:103]
	s_nop 0
	v_cvt_pk_bf16_f32 v102, v96, v97
	v_mul_f32_e32 v97, 0xbfb8aa3b, v98
	v_exp_f32_e32 v97, v97
	v_lshlrev_b32_e32 v96, 16, v107
	v_add_f32_e32 v97, 1.0, v97
	v_rcp_f32_e32 v98, v97
	v_and_b32_e32 v97, 0xffff0000, v107
	v_pk_mul_f32 v[96:97], v[98:99], v[96:97]
	s_nop 0
	v_cvt_pk_bf16_f32 v103, v96, v97
	v_or_b32_e32 v96, 32, v142
	v_ashrrev_i32_e32 v97, 31, v96
	v_lshlrev_b64 v[98:99], 10, v[96:97]
	v_lshl_add_u64 v[98:99], s[34:35], 0, v[98:99]
	v_lshl_add_u64 v[98:99], v[98:99], 0, v[140:141]
	global_store_dwordx4 v[112:113], v[100:103], off offset:256
	v_lshlrev_b64 v[96:97], 11, v[96:97]
	s_waitcnt vmcnt(14)
	v_mov_b64_e32 v[100:101], v[170:171]
	v_mov_b64_e32 v[102:103], v[172:173]
	v_lshlrev_b32_e32 v104, 16, v100
	v_and_b32_e32 v105, 0xffff0000, v100
	v_pk_mul_f32 v[92:93], v[92:93], v[104:105]
	v_lshlrev_b32_e32 v100, 16, v101
	v_cvt_pk_bf16_f32 v92, v92, v93
	v_mul_f32_e32 v93, 0xbfb8aa3b, v94
	v_exp_f32_e32 v93, v93
	v_and_b32_e32 v101, 0xffff0000, v101
	v_add_f32_e32 v93, 1.0, v93
	v_rcp_f32_e32 v94, v93
	v_mul_f32_e32 v93, 0xbfb8aa3b, v95
	v_exp_f32_e32 v93, v93
	s_nop 0
	v_add_f32_e32 v93, 1.0, v93
	v_rcp_f32_e32 v95, v93
	s_nop 0
	v_pk_mul_f32 v[94:95], v[94:95], v[100:101]
	s_nop 0
	v_cvt_pk_bf16_f32 v93, v94, v95
	v_lshlrev_b32_e32 v94, 16, v102
	v_and_b32_e32 v95, 0xffff0000, v102
	v_pk_mul_f32 v[88:89], v[88:89], v[94:95]
	s_nop 0
	v_cvt_pk_bf16_f32 v94, v88, v89
	v_mul_f32_e32 v89, 0xbfb8aa3b, v90
	v_exp_f32_e32 v89, v89
	v_lshlrev_b32_e32 v88, 16, v103
	v_add_f32_e32 v89, 1.0, v89
	v_rcp_f32_e32 v90, v89
	v_and_b32_e32 v89, 0xffff0000, v103
	v_pk_mul_f32 v[88:89], v[90:91], v[88:89]
	s_nop 0
	v_cvt_pk_bf16_f32 v95, v88, v89
	v_lshl_add_u64 v[88:89], s[48:49], 0, v[96:97]
	v_lshl_add_u64 v[88:89], v[88:89], 0, v[140:141]
	global_store_dwordx4 v[88:89], v[92:95], off
	s_waitcnt vmcnt(14)
; __device__ __forceinline__ unsigned pack2(float lo, float hi) { const f32x2_t v = {lo, hi}; const bf16x2_t b = __builtin_convertvector(v, bf16x2_t); return __builtin_bit_cast(unsigned, b); }
; __device__ __forceinline__ float bflo(unsigned w) { return __uint_as_float(w << 16); }
; __device__ __forceinline__ float bfhi(unsigned w) { return __uint_as_float(w & 0xffff0000u); }
; __device__ __forceinline__ float fast_sigmoid(float x) { return __builtin_amdgcn_rcpf(1.0f + __expf(-x)); }
;     __device__ __forceinline__ void operator()(AccRef acc, const Unit& u, int wr, int wc, int fr, int fq, const LAS float* rsl) const {
;     ...
;             for (int m = 0; m < 4; ++m) { const int r = row0 + ai * 128 + m * 16;
; #pragma unroll
;                 for (int bj = 0; bj < 2; ++bj) { const int c = col0 + bj * 128; const f32x4 v0 = acc[ai][bj][m][0], v1 = acc[ai][bj][m][1];
;                     const uint4 gy = *(const uint4*)(GY + (size_t)r * 512 + c); uint4 w;
;                     w.x = pack2(bflo(gy.x) * fast_sigmoid(v0[0]), bfhi(gy.x) * fast_sigmoid(v0[1])); w.y = pack2(bflo(gy.y) * fast_sigmoid(v0[2]), bfhi(gy.y) * fast_sigmoid(v0[3]));
;                     w.z = pack2(bflo(gy.z) * fast_sigmoid(v1[0]), bfhi(gy.z) * fast_sigmoid(v1[1])); w.w = pack2(bflo(gy.w) * fast_sigmoid(v1[2]), bfhi(gy.w) * fast_sigmoid(v1[3]));
;                     *(uint4*)(MIX + (size_t)r * 1024 + c) = w; } }
	v_mov_b64_e32 v[90:91], v[174:175]
	v_mov_b64_e32 v[92:93], v[176:177]
	v_lshlrev_b32_e32 v94, 16, v90
	v_and_b32_e32 v95, 0xffff0000, v90
	v_pk_mul_f32 v[84:85], v[84:85], v[94:95]
	v_lshlrev_b32_e32 v90, 16, v91
	v_cvt_pk_bf16_f32 v84, v84, v85
	v_mul_f32_e32 v85, 0xbfb8aa3b, v86
	v_exp_f32_e32 v85, v85
	v_and_b32_e32 v91, 0xffff0000, v91
	v_add_f32_e32 v85, 1.0, v85
	v_rcp_f32_e32 v86, v85
	v_mul_f32_e32 v85, 0xbfb8aa3b, v87
	v_exp_f32_e32 v85, v85
	s_nop 0
	v_add_f32_e32 v85, 1.0, v85
	v_rcp_f32_e32 v87, v85
	s_nop 0
	v_pk_mul_f32 v[86:87], v[86:87], v[90:91]
	s_nop 0
	v_cvt_pk_bf16_f32 v85, v86, v87
	v_lshlrev_b32_e32 v86, 16, v92
	v_and_b32_e32 v87, 0xffff0000, v92
	v_pk_mul_f32 v[80:81], v[80:81], v[86:87]
	s_nop 0
	v_cvt_pk_bf16_f32 v86, v80, v81
	v_mul_f32_e32 v81, 0xbfb8aa3b, v82
	v_exp_f32_e32 v81, v81
	v_lshlrev_b32_e32 v80, 16, v93
	v_add_f32_e32 v81, 1.0, v81
	v_rcp_f32_e32 v82, v81
	v_and_b32_e32 v81, 0xffff0000, v93
	v_pk_mul_f32 v[80:81], v[82:83], v[80:81]
	s_nop 0
	v_cvt_pk_bf16_f32 v87, v80, v81
	v_or_b32_e32 v80, 48, v142
	v_ashrrev_i32_e32 v81, 31, v80
	v_lshlrev_b64 v[82:83], 10, v[80:81]
	global_store_dwordx4 v[88:89], v[84:87], off offset:256
	s_nop 1
	v_lshlrev_b64 v[86:87], 11, v[80:81]
	v_lshl_add_u64 v[80:81], s[34:35], 0, v[82:83]
	v_lshl_add_u64 v[80:81], v[80:81], 0, v[140:141]
	s_waitcnt vmcnt(14)
	v_mov_b64_e32 v[82:83], v[178:179]
	v_mov_b64_e32 v[84:85], v[180:181]
	v_lshlrev_b32_e32 v88, 16, v82
	v_and_b32_e32 v89, 0xffff0000, v82
	v_pk_mul_f32 v[76:77], v[76:77], v[88:89]
	v_lshlrev_b32_e32 v82, 16, v83
	v_cvt_pk_bf16_f32 v76, v76, v77
	v_mul_f32_e32 v77, 0xbfb8aa3b, v78
	v_exp_f32_e32 v77, v77
	v_and_b32_e32 v83, 0xffff0000, v83
	v_add_f32_e32 v77, 1.0, v77
	v_rcp_f32_e32 v78, v77
	v_mul_f32_e32 v77, 0xbfb8aa3b, v79
	v_exp_f32_e32 v77, v77
	s_nop 0
	v_add_f32_e32 v77, 1.0, v77
	v_rcp_f32_e32 v79, v77
	s_nop 0
	v_pk_mul_f32 v[78:79], v[78:79], v[82:83]
	s_nop 0
	v_cvt_pk_bf16_f32 v77, v78, v79
	v_lshlrev_b32_e32 v78, 16, v84
	v_and_b32_e32 v79, 0xffff0000, v84
	v_pk_mul_f32 v[72:73], v[72:73], v[78:79]
	s_nop 0
	v_cvt_pk_bf16_f32 v78, v72, v73
	v_mul_f32_e32 v73, 0xbfb8aa3b, v74
	v_exp_f32_e32 v73, v73
	v_lshlrev_b32_e32 v72, 16, v85
	v_add_f32_e32 v73, 1.0, v73
	v_rcp_f32_e32 v74, v73
	v_and_b32_e32 v73, 0xffff0000, v85
	v_pk_mul_f32 v[72:73], v[74:75], v[72:73]
	s_nop 0
	v_cvt_pk_bf16_f32 v79, v72, v73
	v_lshl_add_u64 v[72:73], s[48:49], 0, v[86:87]
	v_lshl_add_u64 v[72:73], v[72:73], 0, v[140:141]
	global_store_dwordx4 v[72:73], v[76:79], off
	s_waitcnt vmcnt(14)
	v_mov_b64_e32 v[74:75], v[186:187]
	v_mov_b64_e32 v[76:77], v[188:189]
	v_lshlrev_b32_e32 v78, 16, v74
	v_and_b32_e32 v79, 0xffff0000, v74
	v_pk_mul_f32 v[68:69], v[68:69], v[78:79]
	v_lshlrev_b32_e32 v74, 16, v75
	v_cvt_pk_bf16_f32 v68, v68, v69
	v_mul_f32_e32 v69, 0xbfb8aa3b, v70
	v_exp_f32_e32 v69, v69
	v_and_b32_e32 v75, 0xffff0000, v75
	v_add_f32_e32 v69, 1.0, v69
	v_rcp_f32_e32 v70, v69
	v_mul_f32_e32 v69, 0xbfb8aa3b, v71
	v_exp_f32_e32 v69, v69
	s_nop 0
	v_add_f32_e32 v69, 1.0, v69
	v_rcp_f32_e32 v71, v69
	s_nop 0
	v_pk_mul_f32 v[70:71], v[70:71], v[74:75]
	s_nop 0
	v_cvt_pk_bf16_f32 v69, v70, v71
	v_lshlrev_b32_e32 v70, 16, v76
	v_and_b32_e32 v71, 0xffff0000, v76
	v_pk_mul_f32 v[64:65], v[64:65], v[70:71]
	s_nop 0
	v_cvt_pk_bf16_f32 v70, v64, v65
	v_mul_f32_e32 v65, 0xbfb8aa3b, v66
	v_exp_f32_e32 v65, v65
	v_lshlrev_b32_e32 v64, 16, v77
	v_add_f32_e32 v65, 1.0, v65
	v_rcp_f32_e32 v66, v65
	v_and_b32_e32 v65, 0xffff0000, v77
	v_pk_mul_f32 v[64:65], v[66:67], v[64:65]
	s_nop 0
	v_cvt_pk_bf16_f32 v71, v64, v65
	v_add_u32_e32 v64, 0x80, v142
	v_ashrrev_i32_e32 v65, 31, v64
	v_lshlrev_b64 v[66:67], 10, v[64:65]
	global_store_dwordx4 v[72:73], v[68:71], off offset:256
	s_nop 1
	v_lshlrev_b64 v[70:71], 11, v[64:65]
	v_lshl_add_u64 v[64:65], s[34:35], 0, v[66:67]
	v_lshl_add_u64 v[64:65], v[64:65], 0, v[140:141]
	s_waitcnt vmcnt(14)
	v_mov_b64_e32 v[66:67], v[192:193]
	v_mov_b64_e32 v[68:69], v[194:195]
	v_lshlrev_b32_e32 v72, 16, v66
	v_and_b32_e32 v73, 0xffff0000, v66
	v_pk_mul_f32 v[60:61], v[60:61], v[72:73]
	v_lshlrev_b32_e32 v66, 16, v67
	v_cvt_pk_bf16_f32 v60, v60, v61
	v_mul_f32_e32 v61, 0xbfb8aa3b, v62
	v_exp_f32_e32 v61, v61
	v_and_b32_e32 v67, 0xffff0000, v67
	v_add_f32_e32 v61, 1.0, v61
	v_rcp_f32_e32 v62, v61
	v_mul_f32_e32 v61, 0xbfb8aa3b, v63
	v_exp_f32_e32 v61, v61
	s_nop 0
	v_add_f32_e32 v61, 1.0, v61
	v_rcp_f32_e32 v63, v61
	s_nop 0
	v_pk_mul_f32 v[62:63], v[62:63], v[66:67]
	s_nop 0
	v_cvt_pk_bf16_f32 v61, v62, v63
	v_lshlrev_b32_e32 v62, 16, v68
	v_and_b32_e32 v63, 0xffff0000, v68
	v_pk_mul_f32 v[56:57], v[56:57], v[62:63]
	s_nop 0
	v_cvt_pk_bf16_f32 v62, v56, v57
	v_mul_f32_e32 v57, 0xbfb8aa3b, v58
	v_exp_f32_e32 v57, v57
	v_lshlrev_b32_e32 v56, 16, v69
	v_add_f32_e32 v57, 1.0, v57
	v_rcp_f32_e32 v58, v57
	v_and_b32_e32 v57, 0xffff0000, v69
	v_pk_mul_f32 v[56:57], v[58:59], v[56:57]
	s_nop 0
	v_cvt_pk_bf16_f32 v63, v56, v57
	v_lshl_add_u64 v[56:57], s[48:49], 0, v[70:71]
	v_lshl_add_u64 v[56:57], v[56:57], 0, v[140:141]
	global_store_dwordx4 v[56:57], v[60:63], off
	s_waitcnt vmcnt(14)
; __device__ __forceinline__ unsigned pack2(float lo, float hi) { const f32x2_t v = {lo, hi}; const bf16x2_t b = __builtin_convertvector(v, bf16x2_t); return __builtin_bit_cast(unsigned, b); }
; __device__ __forceinline__ float bflo(unsigned w) { return __uint_as_float(w << 16); }
; __device__ __forceinline__ float bfhi(unsigned w) { return __uint_as_float(w & 0xffff0000u); }
; __device__ __forceinline__ float fast_sigmoid(float x) { return __builtin_amdgcn_rcpf(1.0f + __expf(-x)); }
;     __device__ __forceinline__ void operator()(AccRef acc, const Unit& u, int wr, int wc, int fr, int fq, const LAS float* rsl) const {
;     ...
;             for (int m = 0; m < 4; ++m) { const int r = row0 + ai * 128 + m * 16;
; #pragma unroll
;                 for (int bj = 0; bj < 2; ++bj) { const int c = col0 + bj * 128; const f32x4 v0 = acc[ai][bj][m][0], v1 = acc[ai][bj][m][1];
;                     const uint4 gy = *(const uint4*)(GY + (size_t)r * 512 + c); uint4 w;
;                     w.x = pack2(bflo(gy.x) * fast_sigmoid(v0[0]), bfhi(gy.x) * fast_sigmoid(v0[1])); w.y = pack2(bflo(gy.y) * fast_sigmoid(v0[2]), bfhi(gy.y) * fast_sigmoid(v0[3]));
;                     w.z = pack2(bflo(gy.z) * fast_sigmoid(v1[0]), bfhi(gy.z) * fast_sigmoid(v1[1])); w.w = pack2(bflo(gy.w) * fast_sigmoid(v1[2]), bfhi(gy.w) * fast_sigmoid(v1[3]));
;                     *(uint4*)(MIX + (size_t)r * 1024 + c) = w; } }
	v_mov_b64_e32 v[58:59], v[202:203]
	v_mov_b64_e32 v[60:61], v[204:205]
	v_lshlrev_b32_e32 v62, 16, v58
	v_and_b32_e32 v63, 0xffff0000, v58
	v_pk_mul_f32 v[52:53], v[52:53], v[62:63]
	v_lshlrev_b32_e32 v58, 16, v59
	v_cvt_pk_bf16_f32 v52, v52, v53
	v_mul_f32_e32 v53, 0xbfb8aa3b, v54
	v_exp_f32_e32 v53, v53
	v_and_b32_e32 v59, 0xffff0000, v59
	v_add_f32_e32 v53, 1.0, v53
	v_rcp_f32_e32 v54, v53
	v_mul_f32_e32 v53, 0xbfb8aa3b, v55
	v_exp_f32_e32 v53, v53
	s_nop 0
	v_add_f32_e32 v53, 1.0, v53
	v_rcp_f32_e32 v55, v53
	s_nop 0
	v_pk_mul_f32 v[54:55], v[54:55], v[58:59]
	s_nop 0
	v_cvt_pk_bf16_f32 v53, v54, v55
	v_lshlrev_b32_e32 v54, 16, v60
	v_and_b32_e32 v55, 0xffff0000, v60
	v_pk_mul_f32 v[48:49], v[48:49], v[54:55]
	s_nop 0
	v_cvt_pk_bf16_f32 v54, v48, v49
	v_mul_f32_e32 v49, 0xbfb8aa3b, v50
	v_exp_f32_e32 v49, v49
	v_lshlrev_b32_e32 v48, 16, v61
	v_add_f32_e32 v49, 1.0, v49
	v_rcp_f32_e32 v50, v49
	v_and_b32_e32 v49, 0xffff0000, v61
	v_pk_mul_f32 v[48:49], v[50:51], v[48:49]
	s_nop 0
	v_cvt_pk_bf16_f32 v55, v48, v49
	v_add_u32_e32 v48, 0x90, v142
	v_ashrrev_i32_e32 v49, 31, v48
	v_lshlrev_b64 v[50:51], 10, v[48:49]
	global_store_dwordx4 v[56:57], v[52:55], off offset:256
	s_nop 1
	v_lshlrev_b64 v[54:55], 11, v[48:49]
	v_lshl_add_u64 v[48:49], s[34:35], 0, v[50:51]
	v_lshl_add_u64 v[48:49], v[48:49], 0, v[140:141]
	s_waitcnt vmcnt(14)
	v_mov_b64_e32 v[50:51], v[206:207]
	v_mov_b64_e32 v[52:53], v[208:209]
	v_lshlrev_b32_e32 v56, 16, v50
	v_and_b32_e32 v57, 0xffff0000, v50
	v_pk_mul_f32 v[44:45], v[44:45], v[56:57]
	v_lshlrev_b32_e32 v50, 16, v51
	v_cvt_pk_bf16_f32 v44, v44, v45
	v_mul_f32_e32 v45, 0xbfb8aa3b, v46
	v_exp_f32_e32 v45, v45
	v_and_b32_e32 v51, 0xffff0000, v51
	v_add_f32_e32 v45, 1.0, v45
	v_rcp_f32_e32 v46, v45
	v_mul_f32_e32 v45, 0xbfb8aa3b, v47
	v_exp_f32_e32 v45, v45
	s_nop 0
	v_add_f32_e32 v45, 1.0, v45
	v_rcp_f32_e32 v47, v45
	s_nop 0
	v_pk_mul_f32 v[46:47], v[46:47], v[50:51]
	s_nop 0
	v_cvt_pk_bf16_f32 v45, v46, v47
	v_lshlrev_b32_e32 v46, 16, v52
	v_and_b32_e32 v47, 0xffff0000, v52
	v_pk_mul_f32 v[40:41], v[40:41], v[46:47]
	s_nop 0
	v_cvt_pk_bf16_f32 v46, v40, v41
	v_mul_f32_e32 v41, 0xbfb8aa3b, v42
	v_exp_f32_e32 v41, v41
	v_lshlrev_b32_e32 v40, 16, v53
	v_add_f32_e32 v41, 1.0, v41
	v_rcp_f32_e32 v42, v41
	v_and_b32_e32 v41, 0xffff0000, v53
	v_pk_mul_f32 v[40:41], v[42:43], v[40:41]
	s_nop 0
	v_cvt_pk_bf16_f32 v47, v40, v41
	v_lshl_add_u64 v[40:41], s[48:49], 0, v[54:55]
	v_lshl_add_u64 v[40:41], v[40:41], 0, v[140:141]
	global_store_dwordx4 v[40:41], v[44:47], off
	s_waitcnt vmcnt(14)
	v_mov_b64_e32 v[42:43], v[210:211]
	v_mov_b64_e32 v[44:45], v[212:213]
	v_lshlrev_b32_e32 v46, 16, v42
	v_and_b32_e32 v47, 0xffff0000, v42
	v_pk_mul_f32 v[36:37], v[36:37], v[46:47]
	v_lshlrev_b32_e32 v42, 16, v43
	v_cvt_pk_bf16_f32 v36, v36, v37
	v_mul_f32_e32 v37, 0xbfb8aa3b, v38
	v_exp_f32_e32 v37, v37
	v_and_b32_e32 v43, 0xffff0000, v43
	v_add_f32_e32 v37, 1.0, v37
	v_rcp_f32_e32 v38, v37
	v_mul_f32_e32 v37, 0xbfb8aa3b, v39
	v_exp_f32_e32 v37, v37
	s_nop 0
	v_add_f32_e32 v37, 1.0, v37
	v_rcp_f32_e32 v39, v37
	s_nop 0
	v_pk_mul_f32 v[38:39], v[38:39], v[42:43]
	s_nop 0
	v_cvt_pk_bf16_f32 v37, v38, v39
	v_lshlrev_b32_e32 v38, 16, v44
	v_and_b32_e32 v39, 0xffff0000, v44
	v_pk_mul_f32 v[32:33], v[32:33], v[38:39]
	s_nop 0
	v_cvt_pk_bf16_f32 v38, v32, v33
	v_mul_f32_e32 v33, 0xbfb8aa3b, v34
	v_exp_f32_e32 v33, v33
	v_lshlrev_b32_e32 v32, 16, v45
	v_add_f32_e32 v33, 1.0, v33
	v_rcp_f32_e32 v34, v33
	v_and_b32_e32 v33, 0xffff0000, v45
	v_pk_mul_f32 v[32:33], v[34:35], v[32:33]
	s_nop 0
	v_cvt_pk_bf16_f32 v39, v32, v33
	v_add_u32_e32 v32, 0xa0, v142
	v_ashrrev_i32_e32 v33, 31, v32
	v_lshlrev_b64 v[34:35], 10, v[32:33]
	global_store_dwordx4 v[40:41], v[36:39], off offset:256
	s_nop 1
	v_lshlrev_b64 v[38:39], 11, v[32:33]
	v_lshl_add_u64 v[32:33], s[34:35], 0, v[34:35]
	v_lshl_add_u64 v[32:33], v[32:33], 0, v[140:141]
	s_waitcnt vmcnt(14)
; __device__ __forceinline__ unsigned pack2(float lo, float hi) { const f32x2_t v = {lo, hi}; const bf16x2_t b = __builtin_convertvector(v, bf16x2_t); return __builtin_bit_cast(unsigned, b); }
; __device__ __forceinline__ float bflo(unsigned w) { return __uint_as_float(w << 16); }
; __device__ __forceinline__ float bfhi(unsigned w) { return __uint_as_float(w & 0xffff0000u); }
; __device__ __forceinline__ float fast_sigmoid(float x) { return __builtin_amdgcn_rcpf(1.0f + __expf(-x)); }
;     __device__ __forceinline__ void operator()(AccRef acc, const Unit& u, int wr, int wc, int fr, int fq, const LAS float* rsl) const {
;     ...
;             for (int m = 0; m < 4; ++m) { const int r = row0 + ai * 128 + m * 16;
; #pragma unroll
;                 for (int bj = 0; bj < 2; ++bj) { const int c = col0 + bj * 128; const f32x4 v0 = acc[ai][bj][m][0], v1 = acc[ai][bj][m][1];
;                     const uint4 gy = *(const uint4*)(GY + (size_t)r * 512 + c); uint4 w;
;                     w.x = pack2(bflo(gy.x) * fast_sigmoid(v0[0]), bfhi(gy.x) * fast_sigmoid(v0[1])); w.y = pack2(bflo(gy.y) * fast_sigmoid(v0[2]), bfhi(gy.y) * fast_sigmoid(v0[3]));
;                     w.z = pack2(bflo(gy.z) * fast_sigmoid(v1[0]), bfhi(gy.z) * fast_sigmoid(v1[1])); w.w = pack2(bflo(gy.w) * fast_sigmoid(v1[2]), bfhi(gy.w) * fast_sigmoid(v1[3]));
;                     *(uint4*)(MIX + (size_t)r * 1024 + c) = w; } }
	v_mov_b64_e32 v[34:35], v[214:215]
	v_mov_b64_e32 v[36:37], v[216:217]
	v_lshlrev_b32_e32 v40, 16, v34
	v_and_b32_e32 v41, 0xffff0000, v34
	v_pk_mul_f32 v[28:29], v[28:29], v[40:41]
	v_lshlrev_b32_e32 v34, 16, v35
	v_cvt_pk_bf16_f32 v28, v28, v29
	v_mul_f32_e32 v29, 0xbfb8aa3b, v30
	v_exp_f32_e32 v29, v29
	v_and_b32_e32 v35, 0xffff0000, v35
	v_add_f32_e32 v29, 1.0, v29
	v_rcp_f32_e32 v30, v29
	v_mul_f32_e32 v29, 0xbfb8aa3b, v31
	v_exp_f32_e32 v29, v29
	s_nop 0
	v_add_f32_e32 v29, 1.0, v29
	v_rcp_f32_e32 v31, v29
	s_nop 0
	v_pk_mul_f32 v[30:31], v[30:31], v[34:35]
	s_nop 0
	v_cvt_pk_bf16_f32 v29, v30, v31
	v_lshlrev_b32_e32 v30, 16, v36
	v_and_b32_e32 v31, 0xffff0000, v36
	v_pk_mul_f32 v[24:25], v[24:25], v[30:31]
	s_nop 0
	v_cvt_pk_bf16_f32 v30, v24, v25
	v_mul_f32_e32 v25, 0xbfb8aa3b, v26
	v_exp_f32_e32 v25, v25
	v_lshlrev_b32_e32 v24, 16, v37
	v_add_f32_e32 v25, 1.0, v25
	v_rcp_f32_e32 v26, v25
	v_and_b32_e32 v25, 0xffff0000, v37
	v_pk_mul_f32 v[24:25], v[26:27], v[24:25]
	s_nop 0
	v_cvt_pk_bf16_f32 v31, v24, v25
	v_lshl_add_u64 v[24:25], s[48:49], 0, v[38:39]
	v_lshl_add_u64 v[24:25], v[24:25], 0, v[140:141]
	global_store_dwordx4 v[24:25], v[28:31], off
	s_waitcnt vmcnt(14)
	v_mov_b64_e32 v[26:27], v[218:219]
	v_mov_b64_e32 v[28:29], v[220:221]
	v_lshlrev_b32_e32 v30, 16, v26
	v_and_b32_e32 v31, 0xffff0000, v26
	v_pk_mul_f32 v[20:21], v[20:21], v[30:31]
	v_lshlrev_b32_e32 v26, 16, v27
	v_cvt_pk_bf16_f32 v20, v20, v21
	v_mul_f32_e32 v21, 0xbfb8aa3b, v22
	v_exp_f32_e32 v21, v21
	v_and_b32_e32 v27, 0xffff0000, v27
	v_add_f32_e32 v21, 1.0, v21
	v_rcp_f32_e32 v22, v21
	v_mul_f32_e32 v21, 0xbfb8aa3b, v23
	v_exp_f32_e32 v21, v21
	s_nop 0
	v_add_f32_e32 v21, 1.0, v21
	v_rcp_f32_e32 v23, v21
	s_nop 0
	v_pk_mul_f32 v[22:23], v[22:23], v[26:27]
	s_nop 0
	v_cvt_pk_bf16_f32 v21, v22, v23
	v_lshlrev_b32_e32 v22, 16, v28
	v_and_b32_e32 v23, 0xffff0000, v28
	v_pk_mul_f32 v[16:17], v[16:17], v[22:23]
	s_nop 0
	v_cvt_pk_bf16_f32 v22, v16, v17
	v_mul_f32_e32 v17, 0xbfb8aa3b, v18
	v_exp_f32_e32 v17, v17
	v_lshlrev_b32_e32 v16, 16, v29
	v_add_f32_e32 v17, 1.0, v17
	v_rcp_f32_e32 v18, v17
	v_and_b32_e32 v17, 0xffff0000, v29
	v_pk_mul_f32 v[16:17], v[18:19], v[16:17]
	s_nop 0
	v_cvt_pk_bf16_f32 v23, v16, v17
	v_add_u32_e32 v16, 0xb0, v142
	v_ashrrev_i32_e32 v17, 31, v16
	v_lshlrev_b64 v[18:19], 10, v[16:17]
	global_store_dwordx4 v[24:25], v[20:23], off offset:256
	s_nop 1
	v_lshlrev_b64 v[22:23], 11, v[16:17]
	v_lshl_add_u64 v[16:17], s[34:35], 0, v[18:19]
	v_lshl_add_u64 v[16:17], v[16:17], 0, v[140:141]
	s_waitcnt vmcnt(14)
	v_mov_b64_e32 v[18:19], v[222:223]
	v_mov_b64_e32 v[20:21], v[224:225]
	v_lshlrev_b32_e32 v24, 16, v18
	v_and_b32_e32 v25, 0xffff0000, v18
	v_pk_mul_f32 v[12:13], v[12:13], v[24:25]
	s_nop 0
	v_cvt_pk_bf16_f32 v18, v12, v13
	v_mul_f32_e32 v13, 0xbfb8aa3b, v14
	v_exp_f32_e32 v13, v13
	v_lshlrev_b32_e32 v12, 16, v19
	v_add_f32_e32 v13, 1.0, v13
	v_rcp_f32_e32 v14, v13
	v_and_b32_e32 v13, 0xffff0000, v19
	v_pk_mul_f32 v[12:13], v[14:15], v[12:13]
	s_nop 0
	v_cvt_pk_bf16_f32 v19, v12, v13
	v_lshlrev_b32_e32 v12, 16, v20
	v_and_b32_e32 v13, 0xffff0000, v20
	v_pk_mul_f32 v[8:9], v[8:9], v[12:13]
	s_nop 0
	v_cvt_pk_bf16_f32 v20, v8, v9
	v_mul_f32_e32 v9, 0xbfb8aa3b, v10
	v_exp_f32_e32 v9, v9
	v_lshlrev_b32_e32 v8, 16, v21
	v_add_f32_e32 v9, 1.0, v9
	v_rcp_f32_e32 v10, v9
	v_and_b32_e32 v9, 0xffff0000, v21
	v_pk_mul_f32 v[8:9], v[10:11], v[8:9]
	s_nop 0
	v_cvt_pk_bf16_f32 v21, v8, v9
	v_lshl_add_u64 v[8:9], s[48:49], 0, v[22:23]
	v_lshl_add_u64 v[12:13], v[8:9], 0, v[140:141]
	global_load_dwordx4 v[8:11], v[16:17], off offset:256
	s_waitcnt vmcnt(0)
	v_lshlrev_b32_e32 v14, 16, v8
	v_and_b32_e32 v15, 0xffff0000, v8
	v_pk_mul_f32 v[4:5], v[4:5], v[14:15]
	v_lshlrev_b32_e32 v8, 16, v9
	v_cvt_pk_bf16_f32 v4, v4, v5
	v_mul_f32_e32 v5, 0xbfb8aa3b, v6
	v_exp_f32_e32 v5, v5
	v_and_b32_e32 v9, 0xffff0000, v9
	global_store_dwordx4 v[12:13], v[18:21], off
	v_add_f32_e32 v5, 1.0, v5
	v_rcp_f32_e32 v6, v5
	v_mul_f32_e32 v5, 0xbfb8aa3b, v7
	v_exp_f32_e32 v5, v5
	s_nop 0
	v_add_f32_e32 v5, 1.0, v5
	v_rcp_f32_e32 v7, v5
	s_nop 0
	v_pk_mul_f32 v[6:7], v[6:7], v[8:9]
	s_nop 0
	v_cvt_pk_bf16_f32 v5, v6, v7
	v_lshlrev_b32_e32 v6, 16, v10
	v_and_b32_e32 v7, 0xffff0000, v10
	v_pk_mul_f32 v[0:1], v[0:1], v[6:7]
	s_nop 0
	v_cvt_pk_bf16_f32 v6, v0, v1
	v_mul_f32_e32 v1, 0xbfb8aa3b, v2
	v_exp_f32_e32 v1, v1
	v_lshlrev_b32_e32 v0, 16, v11
	v_add_f32_e32 v1, 1.0, v1
	v_rcp_f32_e32 v2, v1
	v_and_b32_e32 v1, 0xffff0000, v11
	v_pk_mul_f32 v[0:1], v[2:3], v[0:1]
	s_nop 0
	v_cvt_pk_bf16_f32 v7, v0, v1
	global_store_dwordx4 v[12:13], v[4:7], off offset:256
	s_cbranch_vccnz .LBB0_104
	v_readlane_b32 s10, v255, 14
	v_readlane_b32 s11, v255, 15
	s_andn2_b64 vcc, exec, s[10:11]
	s_cbranch_vccnz .LBB0_103
	s_barrier
	s_branch .LBB0_103

; #define LAS __attribute__((address_space(3)))
; __device__ __forceinline__ unsigned pack2(float lo, float hi) { const f32x2_t v = {lo, hi}; const bf16x2_t b = __builtin_convertvector(v, bf16x2_t); return __builtin_bit_cast(unsigned, b); }
; __device__ void transpose_job(const float* __restrict__ src, int K, int Nsrc, bf16_t* __restrict__ dst, int Ndst, int mode, LAS float* tile, int b0, int nb, const float* __restrict__ gain) {
;     ...
;         for (int rr = 0; rr < 8; ++rr) { v[rr] = make_float4(0.f, 0.f, 0.f, 0.f);
;             if (ns0 + c4 + 3 < Nsrc) v[rr] = *(const float4*)(src + (size_t)(k0 + r + rr * 32) * Nsrc + ns0 + c4);
;             if (gain) { const float gk = gain[k0 + r + rr * 32]; v[rr].x *= gk; v[rr].y *= gk; v[rr].z *= gk; v[rr].w *= gk; } }
; #pragma unroll
;         for (int rr = 0; rr < 8; ++rr) { const int kk = r + rr * 32; LAS float* tp = tile + (kk >> 6) * (64 * 65) + (kk & 63) * 65 + c4d;
;             tp[0] = v[rr].x; tp[1] = v[rr].y; tp[2] = v[rr].z; tp[3] = v[rr].w; }
;         __syncthreads();
;         const int n = tid >> 3, kq = (tid & 7) * 8;
; #pragma unroll
;         for (int kt = 0; kt < 4; ++kt) { const LAS float* tp = tile + kt * (64 * 65); uint4 w;
;             w.x = pack2(tp[(kq + 0) * 65 + n], tp[(kq + 1) * 65 + n]); w.y = pack2(tp[(kq + 2) * 65 + n], tp[(kq + 3) * 65 + n]);
;             w.z = pack2(tp[(kq + 4) * 65 + n], tp[(kq + 5) * 65 + n]); w.w = pack2(tp[(kq + 6) * 65 + n], tp[(kq + 7) * 65 + n]);
;             *(uint4*)(dst + (size_t)(n0 + n) * K + k0 + kt * 64 + kq) = w; }
;         __syncthreads();
.LBB0_644:
	s_waitcnt vmcnt(0)
	s_and_b64 vcc, exec, s[42:43]
	s_cbranch_vccnz .Lwcvt_ns0
	v_pk_mul_f32 v[0:1], v[0:1], v[60:61] op_sel_hi:[1,0]
	v_pk_mul_f32 v[2:3], v[2:3], v[60:61] op_sel_hi:[1,0]
	v_pk_mul_f32 v[4:5], v[4:5], v[62:63] op_sel_hi:[1,0]
	v_pk_mul_f32 v[6:7], v[6:7], v[62:63] op_sel_hi:[1,0]
	v_pk_mul_f32 v[8:9], v[8:9], v[64:65] op_sel_hi:[1,0]
	v_pk_mul_f32 v[10:11], v[10:11], v[64:65] op_sel_hi:[1,0]
	v_pk_mul_f32 v[12:13], v[12:13], v[66:67] op_sel_hi:[1,0]
	v_pk_mul_f32 v[14:15], v[14:15], v[66:67] op_sel_hi:[1,0]
	v_pk_mul_f32 v[16:17], v[16:17], v[68:69] op_sel_hi:[1,0]
	v_pk_mul_f32 v[18:19], v[18:19], v[68:69] op_sel_hi:[1,0]
	v_pk_mul_f32 v[20:21], v[20:21], v[70:71] op_sel_hi:[1,0]
	v_pk_mul_f32 v[22:23], v[22:23], v[70:71] op_sel_hi:[1,0]
	v_pk_mul_f32 v[24:25], v[24:25], v[72:73] op_sel_hi:[1,0]
	v_pk_mul_f32 v[26:27], v[26:27], v[72:73] op_sel_hi:[1,0]
	v_pk_mul_f32 v[28:29], v[28:29], v[74:75] op_sel_hi:[1,0]
	v_pk_mul_f32 v[30:31], v[30:31], v[74:75] op_sel_hi:[1,0]
.Lwcvt_ns0:
	ds_write2_b32 v43, v0, v1 offset1:1
	ds_write2_b32 v43, v2, v3 offset0:2 offset1:3
	ds_write2_b32 v44, v4, v5 offset1:1
	ds_write2_b32 v44, v6, v7 offset0:2 offset1:3
	ds_write2_b32 v45, v8, v9 offset1:1
	ds_write2_b32 v45, v10, v11 offset0:2 offset1:3
	ds_write2_b32 v46, v12, v13 offset1:1
	ds_write2_b32 v46, v14, v15 offset0:2 offset1:3
	ds_write2_b32 v47, v16, v17 offset1:1
	ds_write2_b32 v47, v18, v19 offset0:2 offset1:3
	ds_write2_b32 v48, v20, v21 offset1:1
	ds_write2_b32 v48, v22, v23 offset0:2 offset1:3
	ds_write2_b32 v49, v24, v25 offset1:1
	ds_write2_b32 v49, v26, v27 offset0:2 offset1:3
	ds_write2_b32 v50, v28, v29 offset1:1
	ds_write2_b32 v50, v30, v31 offset0:2 offset1:3
	v_add_u32_e32 v8, 0x400, v42
	s_waitcnt lgkmcnt(0)
	s_barrier
	v_add_u32_e32 v0, s27, v41
	ds_read2_b32 v[2:3], v42 offset1:65
	ds_read2_b32 v[4:5], v42 offset0:130 offset1:195
	ds_read2_b32 v[6:7], v8 offset0:4 offset1:69
	ds_read2_b32 v[8:9], v8 offset0:134 offset1:199
	s_sub_i32 s18, 0, s28
	v_ashrrev_i32_e32 v1, 31, v0
	s_add_i32 s18, s23, s18
	v_lshlrev_b64 v[0:1], 11, v[0:1]
	v_lshl_add_u64 v[0:1], s[14:15], 0, v[0:1]
	s_ashr_i32 s19, s18, 31
	v_lshl_add_u64 v[0:1], s[18:19], 1, v[0:1]
	v_mov_b32_e32 v35, v184
	v_lshl_add_u64 v[10:11], v[0:1], 0, v[34:35]
	s_waitcnt lgkmcnt(3)
	v_cvt_pk_bf16_f32 v0, v2, v3
	s_waitcnt lgkmcnt(2)
	v_cvt_pk_bf16_f32 v1, v4, v5
	s_waitcnt lgkmcnt(0)
	v_cvt_pk_bf16_f32 v3, v8, v9
	v_add_u32_e32 v4, 0x4000, v42
	v_add_u32_e32 v8, 0x4400, v42
	v_add_u32_e32 v12, 0x4600, v42
	v_cvt_pk_bf16_f32 v2, v6, v7
	ds_read2_b32 v[4:5], v4 offset0:64 offset1:129
	v_add_u32_e32 v6, 0x4200, v42
	ds_read2_b32 v[8:9], v8 offset0:68 offset1:133
	ds_read2_b32 v[12:13], v12 offset0:70 offset1:135
	ds_read2_b32 v[6:7], v6 offset0:66 offset1:131
	global_store_dwordx4 v[10:11], v[0:3], off
	s_add_i32 s22, s22, s25
	s_add_i32 s23, s23, s26
	s_waitcnt lgkmcnt(3)
	v_cvt_pk_bf16_f32 v0, v4, v5
	s_waitcnt lgkmcnt(2)
	v_cvt_pk_bf16_f32 v2, v8, v9
	s_waitcnt lgkmcnt(1)
	v_cvt_pk_bf16_f32 v3, v12, v13
	v_add_u32_e32 v4, 0x8000, v42
	v_add_u32_e32 v8, 0x8400, v42
	v_add_u32_e32 v12, 0x8800, v42
	s_waitcnt lgkmcnt(0)
	v_cvt_pk_bf16_f32 v1, v6, v7
	ds_read2_b32 v[4:5], v4 offset0:128 offset1:193
	ds_read2_b32 v[6:7], v8 offset0:2 offset1:67
	ds_read2_b32 v[8:9], v8 offset0:132 offset1:197
	ds_read2_b32 v[12:13], v12 offset0:6 offset1:71
	global_store_dwordx4 v[10:11], v[0:3], off offset:128
	s_cmpk_lt_i32 s22, 0x160
	s_waitcnt lgkmcnt(3)
	v_cvt_pk_bf16_f32 v0, v4, v5
	s_waitcnt lgkmcnt(2)
	v_cvt_pk_bf16_f32 v1, v6, v7
	s_waitcnt lgkmcnt(1)
	v_cvt_pk_bf16_f32 v2, v8, v9
	s_waitcnt lgkmcnt(0)
	v_cvt_pk_bf16_f32 v3, v12, v13
	v_add_u32_e32 v4, 0xc200, v42
	v_add_u32_e32 v6, 0xc400, v42
	v_add_u32_e32 v8, 0xc600, v42
	v_add_u32_e32 v12, 0xc800, v42
	ds_read2_b32 v[4:5], v4 offset0:64 offset1:129
	ds_read2_b32 v[6:7], v6 offset0:66 offset1:131
	ds_read2_b32 v[8:9], v8 offset0:68 offset1:133
	ds_read2_b32 v[12:13], v12 offset0:70 offset1:135
	global_store_dwordx4 v[10:11], v[0:3], off offset:256
	s_waitcnt lgkmcnt(3)
	s_nop 0
	v_cvt_pk_bf16_f32 v0, v4, v5
	s_waitcnt lgkmcnt(2)
	v_cvt_pk_bf16_f32 v1, v6, v7
	s_waitcnt lgkmcnt(1)
	v_cvt_pk_bf16_f32 v2, v8, v9
	s_waitcnt lgkmcnt(0)
	v_cvt_pk_bf16_f32 v3, v12, v13
	global_store_dwordx4 v[10:11], v[0:3], off offset:384
	s_barrier
	s_cbranch_scc0 .LBB0_677

; __device__ void transpose_job(const float* __restrict__ src, int K, int Nsrc, bf16_t* __restrict__ dst, int Ndst, int mode, LAS float* tile, int b0, int nb, const float* __restrict__ gain) {
;     ...
;         for (int rr = 0; rr < 8; ++rr) { v[rr] = make_float4(0.f, 0.f, 0.f, 0.f);
;             if (ns0 + c4 + 3 < Nsrc) v[rr] = *(const float4*)(src + (size_t)(k0 + r + rr * 32) * Nsrc + ns0 + c4);
;             if (gain) { const float gk = gain[k0 + r + rr * 32]; v[rr].x *= gk; v[rr].y *= gk; v[rr].z *= gk; v[rr].w *= gk; } }
.LBB0_647:
	s_or_b64 exec, exec, s[18:19]
	v_cndmask_b32_e64 v4, 0, 1, s[8:9]
	v_cmp_ne_u32_e64 s[42:43], 1, v4
	s_andn2_b64 vcc, exec, s[8:9]
	v_ashrrev_i32_e32 v37, 31, v36
	s_cbranch_vccnz .LBB0_649
	v_lshl_add_u64 v[76:77], v[36:37], 2, s[16:17]
	global_load_dword v60, v[76:77], off

; __device__ void transpose_job(const float* __restrict__ src, int K, int Nsrc, bf16_t* __restrict__ dst, int Ndst, int mode, LAS float* tile, int b0, int nb, const float* __restrict__ gain) {
;     ...
;         for (int rr = 0; rr < 8; ++rr) { v[rr] = make_float4(0.f, 0.f, 0.f, 0.f);
;             if (ns0 + c4 + 3 < Nsrc) v[rr] = *(const float4*)(src + (size_t)(k0 + r + rr * 32) * Nsrc + ns0 + c4);
;             if (gain) { const float gk = gain[k0 + r + rr * 32]; v[rr].x *= gk; v[rr].y *= gk; v[rr].z *= gk; v[rr].w *= gk; } }
.LBB0_651:
	s_or_b64 exec, exec, s[18:19]
	s_and_b64 vcc, exec, s[42:43]
	s_cbranch_vccnz .LBB0_653
	v_lshl_add_u64 v[76:77], v[36:37], 2, s[16:17]
	global_load_dword v62, v[76:77], off offset:128

; __device__ void transpose_job(const float* __restrict__ src, int K, int Nsrc, bf16_t* __restrict__ dst, int Ndst, int mode, LAS float* tile, int b0, int nb, const float* __restrict__ gain) {
;     ...
;         for (int rr = 0; rr < 8; ++rr) { v[rr] = make_float4(0.f, 0.f, 0.f, 0.f);
;             if (ns0 + c4 + 3 < Nsrc) v[rr] = *(const float4*)(src + (size_t)(k0 + r + rr * 32) * Nsrc + ns0 + c4);
;             if (gain) { const float gk = gain[k0 + r + rr * 32]; v[rr].x *= gk; v[rr].y *= gk; v[rr].z *= gk; v[rr].w *= gk; } }
.LBB0_655:
	s_or_b64 exec, exec, s[18:19]
	s_and_b64 vcc, exec, s[42:43]
	s_cbranch_vccnz .LBB0_657
	v_lshl_add_u64 v[76:77], v[36:37], 2, s[16:17]
	global_load_dword v64, v[76:77], off offset:256

; __device__ void transpose_job(const float* __restrict__ src, int K, int Nsrc, bf16_t* __restrict__ dst, int Ndst, int mode, LAS float* tile, int b0, int nb, const float* __restrict__ gain) {
;     ...
;         for (int rr = 0; rr < 8; ++rr) { v[rr] = make_float4(0.f, 0.f, 0.f, 0.f);
;             if (ns0 + c4 + 3 < Nsrc) v[rr] = *(const float4*)(src + (size_t)(k0 + r + rr * 32) * Nsrc + ns0 + c4);
;             if (gain) { const float gk = gain[k0 + r + rr * 32]; v[rr].x *= gk; v[rr].y *= gk; v[rr].z *= gk; v[rr].w *= gk; } }
.LBB0_659:
	s_or_b64 exec, exec, s[18:19]
	s_and_b64 vcc, exec, s[42:43]
	s_cbranch_vccnz .LBB0_661
	v_lshl_add_u64 v[76:77], v[36:37], 2, s[16:17]
	global_load_dword v66, v[76:77], off offset:384

; __device__ void transpose_job(const float* __restrict__ src, int K, int Nsrc, bf16_t* __restrict__ dst, int Ndst, int mode, LAS float* tile, int b0, int nb, const float* __restrict__ gain) {
;     ...
;         for (int rr = 0; rr < 8; ++rr) { v[rr] = make_float4(0.f, 0.f, 0.f, 0.f);
;             if (ns0 + c4 + 3 < Nsrc) v[rr] = *(const float4*)(src + (size_t)(k0 + r + rr * 32) * Nsrc + ns0 + c4);
;             if (gain) { const float gk = gain[k0 + r + rr * 32]; v[rr].x *= gk; v[rr].y *= gk; v[rr].z *= gk; v[rr].w *= gk; } }
.LBB0_663:
	s_or_b64 exec, exec, s[18:19]
	s_and_b64 vcc, exec, s[42:43]
	s_cbranch_vccnz .LBB0_665
	v_lshl_add_u64 v[76:77], v[36:37], 2, s[16:17]
	global_load_dword v68, v[76:77], off offset:512

; __device__ void transpose_job(const float* __restrict__ src, int K, int Nsrc, bf16_t* __restrict__ dst, int Ndst, int mode, LAS float* tile, int b0, int nb, const float* __restrict__ gain) {
;     ...
;         for (int rr = 0; rr < 8; ++rr) { v[rr] = make_float4(0.f, 0.f, 0.f, 0.f);
;             if (ns0 + c4 + 3 < Nsrc) v[rr] = *(const float4*)(src + (size_t)(k0 + r + rr * 32) * Nsrc + ns0 + c4);
;             if (gain) { const float gk = gain[k0 + r + rr * 32]; v[rr].x *= gk; v[rr].y *= gk; v[rr].z *= gk; v[rr].w *= gk; } }
.LBB0_667:
	s_or_b64 exec, exec, s[18:19]
	s_and_b64 vcc, exec, s[42:43]
	s_cbranch_vccnz .LBB0_669
	v_lshl_add_u64 v[76:77], v[36:37], 2, s[16:17]
	global_load_dword v70, v[76:77], off offset:640

; __device__ void transpose_job(const float* __restrict__ src, int K, int Nsrc, bf16_t* __restrict__ dst, int Ndst, int mode, LAS float* tile, int b0, int nb, const float* __restrict__ gain) {
;     ...
;         for (int rr = 0; rr < 8; ++rr) { v[rr] = make_float4(0.f, 0.f, 0.f, 0.f);
;             if (ns0 + c4 + 3 < Nsrc) v[rr] = *(const float4*)(src + (size_t)(k0 + r + rr * 32) * Nsrc + ns0 + c4);
;             if (gain) { const float gk = gain[k0 + r + rr * 32]; v[rr].x *= gk; v[rr].y *= gk; v[rr].z *= gk; v[rr].w *= gk; } }
.LBB0_671:
	s_or_b64 exec, exec, s[18:19]
	s_and_b64 vcc, exec, s[42:43]
	s_cbranch_vccnz .LBB0_673
	v_lshl_add_u64 v[76:77], v[36:37], 2, s[16:17]
	global_load_dword v72, v[76:77], off offset:768

; __device__ void transpose_job(const float* __restrict__ src, int K, int Nsrc, bf16_t* __restrict__ dst, int Ndst, int mode, LAS float* tile, int b0, int nb, const float* __restrict__ gain) {
;     ...
;         for (int rr = 0; rr < 8; ++rr) { v[rr] = make_float4(0.f, 0.f, 0.f, 0.f);
;             if (ns0 + c4 + 3 < Nsrc) v[rr] = *(const float4*)(src + (size_t)(k0 + r + rr * 32) * Nsrc + ns0 + c4);
;             if (gain) { const float gk = gain[k0 + r + rr * 32]; v[rr].x *= gk; v[rr].y *= gk; v[rr].z *= gk; v[rr].w *= gk; } }
.LBB0_675:
	s_or_b64 exec, exec, s[18:19]
	s_and_b64 vcc, exec, s[42:43]
	s_cbranch_vccnz .LBB0_644
	v_lshl_add_u64 v[76:77], v[36:37], 2, s[16:17]
	global_load_dword v74, v[76:77], off offset:896
	s_branch .LBB0_644

; #define LAS __attribute__((address_space(3)))
; __device__ __forceinline__ unsigned pack2(float lo, float hi) { const f32x2_t v = {lo, hi}; const bf16x2_t b = __builtin_convertvector(v, bf16x2_t); return __builtin_bit_cast(unsigned, b); }
; __device__ void transpose_job(const float* __restrict__ src, int K, int Nsrc, bf16_t* __restrict__ dst, int Ndst, int mode, LAS float* tile, int b0, int nb, const float* __restrict__ gain) {
;     ...
;         for (int rr = 0; rr < 8; ++rr) { const int kk = r + rr * 32; LAS float* tp = tile + (kk >> 6) * (64 * 65) + (kk & 63) * 65 + c4d;
;             tp[0] = v[rr].x; tp[1] = v[rr].y; tp[2] = v[rr].z; tp[3] = v[rr].w; }
;         __syncthreads();
;         const int n = tid >> 3, kq = (tid & 7) * 8;
; #pragma unroll
;         for (int kt = 0; kt < 4; ++kt) { const LAS float* tp = tile + kt * (64 * 65); uint4 w;
;             w.x = pack2(tp[(kq + 0) * 65 + n], tp[(kq + 1) * 65 + n]); w.y = pack2(tp[(kq + 2) * 65 + n], tp[(kq + 3) * 65 + n]);
;             w.z = pack2(tp[(kq + 4) * 65 + n], tp[(kq + 5) * 65 + n]); w.w = pack2(tp[(kq + 6) * 65 + n], tp[(kq + 7) * 65 + n]);
;             *(uint4*)(dst + (size_t)(n0 + n) * K + k0 + kt * 64 + kq) = w; }
;         __syncthreads();
.Lwcvt_ns1:
	ds_write2_b32 v43, v0, v1 offset1:1
	ds_write2_b32 v43, v2, v3 offset0:2 offset1:3
	ds_write2_b32 v44, v4, v5 offset1:1
	ds_write2_b32 v44, v6, v7 offset0:2 offset1:3
	ds_write2_b32 v45, v8, v9 offset1:1
	ds_write2_b32 v45, v10, v11 offset0:2 offset1:3
	ds_write2_b32 v46, v12, v13 offset1:1
	ds_write2_b32 v46, v14, v15 offset0:2 offset1:3
	ds_write2_b32 v47, v16, v17 offset1:1
	ds_write2_b32 v47, v18, v19 offset0:2 offset1:3
	ds_write2_b32 v48, v20, v21 offset1:1
	ds_write2_b32 v48, v22, v23 offset0:2 offset1:3
	ds_write2_b32 v49, v24, v25 offset1:1
	ds_write2_b32 v49, v26, v27 offset0:2 offset1:3
	ds_write2_b32 v50, v28, v29 offset1:1
	ds_write2_b32 v50, v30, v31 offset0:2 offset1:3
	v_add_u32_e32 v8, 0x400, v42
	s_waitcnt lgkmcnt(0)
	s_barrier
	v_add_u32_e32 v0, s28, v41
	ds_read2_b32 v[2:3], v42 offset1:65
	ds_read2_b32 v[4:5], v42 offset0:130 offset1:195
	ds_read2_b32 v[6:7], v8 offset0:4 offset1:69
	ds_read2_b32 v[8:9], v8 offset0:134 offset1:199
	s_sub_i32 s18, 0, s29
	v_ashrrev_i32_e32 v1, 31, v0
	s_add_i32 s18, s26, s18
	v_lshlrev_b64 v[0:1], 11, v[0:1]
	v_lshl_add_u64 v[0:1], s[14:15], 0, v[0:1]
	s_ashr_i32 s19, s18, 31
	v_lshl_add_u64 v[0:1], s[18:19], 1, v[0:1]
	v_mov_b32_e32 v35, v184
	v_lshl_add_u64 v[10:11], v[0:1], 0, v[34:35]
	s_waitcnt lgkmcnt(3)
	v_cvt_pk_bf16_f32 v0, v2, v3
	s_waitcnt lgkmcnt(2)
	v_cvt_pk_bf16_f32 v1, v4, v5
	s_waitcnt lgkmcnt(0)
	v_cvt_pk_bf16_f32 v3, v8, v9
	v_add_u32_e32 v4, 0x4000, v42
	v_add_u32_e32 v8, 0x4400, v42
	v_add_u32_e32 v12, 0x4600, v42
	v_cvt_pk_bf16_f32 v2, v6, v7
	ds_read2_b32 v[4:5], v4 offset0:64 offset1:129
	v_add_u32_e32 v6, 0x4200, v42
	ds_read2_b32 v[8:9], v8 offset0:68 offset1:133
	ds_read2_b32 v[12:13], v12 offset0:70 offset1:135
	ds_read2_b32 v[6:7], v6 offset0:66 offset1:131
	global_store_dwordx4 v[10:11], v[0:3], off
	s_add_i32 s23, s23, s25
	s_add_i32 s26, s26, s27
	s_waitcnt lgkmcnt(3)
	v_cvt_pk_bf16_f32 v0, v4, v5
	s_waitcnt lgkmcnt(2)
	v_cvt_pk_bf16_f32 v2, v8, v9
	s_waitcnt lgkmcnt(1)
	v_cvt_pk_bf16_f32 v3, v12, v13
	v_add_u32_e32 v4, 0x8000, v42
	v_add_u32_e32 v8, 0x8400, v42
	v_add_u32_e32 v12, 0x8800, v42
	s_waitcnt lgkmcnt(0)
	v_cvt_pk_bf16_f32 v1, v6, v7
	ds_read2_b32 v[4:5], v4 offset0:128 offset1:193
	ds_read2_b32 v[6:7], v8 offset0:2 offset1:67
	ds_read2_b32 v[8:9], v8 offset0:132 offset1:197
	ds_read2_b32 v[12:13], v12 offset0:6 offset1:71
	global_store_dwordx4 v[10:11], v[0:3], off offset:128
	s_cmpk_lt_i32 s23, 0x160
	s_waitcnt lgkmcnt(3)
	v_cvt_pk_bf16_f32 v0, v4, v5
	s_waitcnt lgkmcnt(2)
	v_cvt_pk_bf16_f32 v1, v6, v7
	s_waitcnt lgkmcnt(1)
	v_cvt_pk_bf16_f32 v2, v8, v9
	s_waitcnt lgkmcnt(0)
	v_cvt_pk_bf16_f32 v3, v12, v13
	v_add_u32_e32 v4, 0xc200, v42
	v_add_u32_e32 v6, 0xc400, v42
	v_add_u32_e32 v8, 0xc600, v42
	v_add_u32_e32 v12, 0xc800, v42
	ds_read2_b32 v[4:5], v4 offset0:64 offset1:129
	ds_read2_b32 v[6:7], v6 offset0:66 offset1:131
	ds_read2_b32 v[8:9], v8 offset0:68 offset1:133
	ds_read2_b32 v[12:13], v12 offset0:70 offset1:135
	global_store_dwordx4 v[10:11], v[0:3], off offset:256
	s_waitcnt lgkmcnt(3)
	s_nop 0
	v_cvt_pk_bf16_f32 v0, v4, v5
	s_waitcnt lgkmcnt(2)
	v_cvt_pk_bf16_f32 v1, v6, v7
	s_waitcnt lgkmcnt(1)
	v_cvt_pk_bf16_f32 v2, v8, v9
	s_waitcnt lgkmcnt(0)
	v_cvt_pk_bf16_f32 v3, v12, v13
	global_store_dwordx4 v[10:11], v[0:3], off offset:384
	s_barrier
	s_cbranch_scc0 .LBB0_712

; __device__ void transpose_job(const float* __restrict__ src, int K, int Nsrc, bf16_t* __restrict__ dst, int Ndst, int mode, LAS float* tile, int b0, int nb, const float* __restrict__ gain) {
;     ...
;         for (int rr = 0; rr < 8; ++rr) { v[rr] = make_float4(0.f, 0.f, 0.f, 0.f);
;             if (ns0 + c4 + 3 < Nsrc) v[rr] = *(const float4*)(src + (size_t)(k0 + r + rr * 32) * Nsrc + ns0 + c4);
;             if (gain) { const float gk = gain[k0 + r + rr * 32]; v[rr].x *= gk; v[rr].y *= gk; v[rr].z *= gk; v[rr].w *= gk; } }
.LBB0_682:
	s_or_b64 exec, exec, s[18:19]
	v_cndmask_b32_e64 v4, 0, 1, s[16:17]
	v_cmp_ne_u32_e64 s[42:43], 1, v4
	s_andn2_b64 vcc, exec, s[16:17]
	v_ashrrev_i32_e32 v37, 31, v36
	s_cbranch_vccnz .LBB0_684
	v_lshl_add_u64 v[76:77], v[36:37], 2, s[12:13]
	global_load_dword v60, v[76:77], off

; __device__ void transpose_job(const float* __restrict__ src, int K, int Nsrc, bf16_t* __restrict__ dst, int Ndst, int mode, LAS float* tile, int b0, int nb, const float* __restrict__ gain) {
;     ...
;         for (int rr = 0; rr < 8; ++rr) { v[rr] = make_float4(0.f, 0.f, 0.f, 0.f);
;             if (ns0 + c4 + 3 < Nsrc) v[rr] = *(const float4*)(src + (size_t)(k0 + r + rr * 32) * Nsrc + ns0 + c4);
;             if (gain) { const float gk = gain[k0 + r + rr * 32]; v[rr].x *= gk; v[rr].y *= gk; v[rr].z *= gk; v[rr].w *= gk; } }
.LBB0_686:
	s_or_b64 exec, exec, s[18:19]
	s_and_b64 vcc, exec, s[42:43]
	s_cbranch_vccnz .LBB0_688
	v_lshl_add_u64 v[76:77], v[36:37], 2, s[12:13]
	global_load_dword v62, v[76:77], off offset:128

; __device__ void transpose_job(const float* __restrict__ src, int K, int Nsrc, bf16_t* __restrict__ dst, int Ndst, int mode, LAS float* tile, int b0, int nb, const float* __restrict__ gain) {
;     ...
;         for (int rr = 0; rr < 8; ++rr) { v[rr] = make_float4(0.f, 0.f, 0.f, 0.f);
;             if (ns0 + c4 + 3 < Nsrc) v[rr] = *(const float4*)(src + (size_t)(k0 + r + rr * 32) * Nsrc + ns0 + c4);
;             if (gain) { const float gk = gain[k0 + r + rr * 32]; v[rr].x *= gk; v[rr].y *= gk; v[rr].z *= gk; v[rr].w *= gk; } }
.LBB0_690:
	s_or_b64 exec, exec, s[18:19]
	s_and_b64 vcc, exec, s[42:43]
	s_cbranch_vccnz .LBB0_692
	v_lshl_add_u64 v[76:77], v[36:37], 2, s[12:13]
	global_load_dword v64, v[76:77], off offset:256

; __device__ void transpose_job(const float* __restrict__ src, int K, int Nsrc, bf16_t* __restrict__ dst, int Ndst, int mode, LAS float* tile, int b0, int nb, const float* __restrict__ gain) {
;     ...
;         for (int rr = 0; rr < 8; ++rr) { v[rr] = make_float4(0.f, 0.f, 0.f, 0.f);
;             if (ns0 + c4 + 3 < Nsrc) v[rr] = *(const float4*)(src + (size_t)(k0 + r + rr * 32) * Nsrc + ns0 + c4);
;             if (gain) { const float gk = gain[k0 + r + rr * 32]; v[rr].x *= gk; v[rr].y *= gk; v[rr].z *= gk; v[rr].w *= gk; } }
.LBB0_694:
	s_or_b64 exec, exec, s[18:19]
	s_and_b64 vcc, exec, s[42:43]
	s_cbranch_vccnz .LBB0_696
	v_lshl_add_u64 v[76:77], v[36:37], 2, s[12:13]
	global_load_dword v66, v[76:77], off offset:384

; __device__ void transpose_job(const float* __restrict__ src, int K, int Nsrc, bf16_t* __restrict__ dst, int Ndst, int mode, LAS float* tile, int b0, int nb, const float* __restrict__ gain) {
;     ...
;         for (int rr = 0; rr < 8; ++rr) { v[rr] = make_float4(0.f, 0.f, 0.f, 0.f);
;             if (ns0 + c4 + 3 < Nsrc) v[rr] = *(const float4*)(src + (size_t)(k0 + r + rr * 32) * Nsrc + ns0 + c4);
;             if (gain) { const float gk = gain[k0 + r + rr * 32]; v[rr].x *= gk; v[rr].y *= gk; v[rr].z *= gk; v[rr].w *= gk; } }
.LBB0_698:
	s_or_b64 exec, exec, s[18:19]
	s_and_b64 vcc, exec, s[42:43]
	s_cbranch_vccnz .LBB0_700
	v_lshl_add_u64 v[76:77], v[36:37], 2, s[12:13]
	global_load_dword v68, v[76:77], off offset:512

; __device__ void transpose_job(const float* __restrict__ src, int K, int Nsrc, bf16_t* __restrict__ dst, int Ndst, int mode, LAS float* tile, int b0, int nb, const float* __restrict__ gain) {
;     ...
;         for (int rr = 0; rr < 8; ++rr) { v[rr] = make_float4(0.f, 0.f, 0.f, 0.f);
;             if (ns0 + c4 + 3 < Nsrc) v[rr] = *(const float4*)(src + (size_t)(k0 + r + rr * 32) * Nsrc + ns0 + c4);
;             if (gain) { const float gk = gain[k0 + r + rr * 32]; v[rr].x *= gk; v[rr].y *= gk; v[rr].z *= gk; v[rr].w *= gk; } }
.LBB0_702:
	s_or_b64 exec, exec, s[18:19]
	s_and_b64 vcc, exec, s[42:43]
	s_cbranch_vccnz .LBB0_704
	v_lshl_add_u64 v[76:77], v[36:37], 2, s[12:13]
	global_load_dword v70, v[76:77], off offset:640

; __device__ void transpose_job(const float* __restrict__ src, int K, int Nsrc, bf16_t* __restrict__ dst, int Ndst, int mode, LAS float* tile, int b0, int nb, const float* __restrict__ gain) {
;     ...
;         for (int rr = 0; rr < 8; ++rr) { v[rr] = make_float4(0.f, 0.f, 0.f, 0.f);
;             if (ns0 + c4 + 3 < Nsrc) v[rr] = *(const float4*)(src + (size_t)(k0 + r + rr * 32) * Nsrc + ns0 + c4);
;             if (gain) { const float gk = gain[k0 + r + rr * 32]; v[rr].x *= gk; v[rr].y *= gk; v[rr].z *= gk; v[rr].w *= gk; } }
.LBB0_706:
	s_or_b64 exec, exec, s[18:19]
	s_and_b64 vcc, exec, s[42:43]
	s_cbranch_vccnz .LBB0_708
	v_lshl_add_u64 v[76:77], v[36:37], 2, s[12:13]
	global_load_dword v72, v[76:77], off offset:768

; __device__ void transpose_job(const float* __restrict__ src, int K, int Nsrc, bf16_t* __restrict__ dst, int Ndst, int mode, LAS float* tile, int b0, int nb, const float* __restrict__ gain) {
;     ...
;         for (int rr = 0; rr < 8; ++rr) { v[rr] = make_float4(0.f, 0.f, 0.f, 0.f);
;             if (ns0 + c4 + 3 < Nsrc) v[rr] = *(const float4*)(src + (size_t)(k0 + r + rr * 32) * Nsrc + ns0 + c4);
;             if (gain) { const float gk = gain[k0 + r + rr * 32]; v[rr].x *= gk; v[rr].y *= gk; v[rr].z *= gk; v[rr].w *= gk; } }
.LBB0_710:
	s_or_b64 exec, exec, s[18:19]
	s_and_b64 vcc, exec, s[42:43]
	s_cbranch_vccnz .LBB0_679
	v_lshl_add_u64 v[76:77], v[36:37], 2, s[12:13]
	global_load_dword v74, v[76:77], off offset:896
	s_branch .LBB0_679

; #define LAS __attribute__((address_space(3)))
; __device__ __forceinline__ unsigned pack2(float lo, float hi) { const f32x2_t v = {lo, hi}; const bf16x2_t b = __builtin_convertvector(v, bf16x2_t); return __builtin_bit_cast(unsigned, b); }
; __device__ void transpose_job(const float* __restrict__ src, int K, int Nsrc, bf16_t* __restrict__ dst, int Ndst, int mode, LAS float* tile, int b0, int nb, const float* __restrict__ gain) {
;     ...
;         for (int rr = 0; rr < 8; ++rr) { const int kk = r + rr * 32; LAS float* tp = tile + (kk >> 6) * (64 * 65) + (kk & 63) * 65 + c4d;
;             tp[0] = v[rr].x; tp[1] = v[rr].y; tp[2] = v[rr].z; tp[3] = v[rr].w; }
;         __syncthreads();
;         const int n = tid >> 3, kq = (tid & 7) * 8;
; #pragma unroll
;         for (int kt = 0; kt < 4; ++kt) { const LAS float* tp = tile + kt * (64 * 65); uint4 w;
;             w.x = pack2(tp[(kq + 0) * 65 + n], tp[(kq + 1) * 65 + n]); w.y = pack2(tp[(kq + 2) * 65 + n], tp[(kq + 3) * 65 + n]);
;             w.z = pack2(tp[(kq + 4) * 65 + n], tp[(kq + 5) * 65 + n]); w.w = pack2(tp[(kq + 6) * 65 + n], tp[(kq + 7) * 65 + n]);
;             *(uint4*)(dst + (size_t)(n0 + n) * K + k0 + kt * 64 + kq) = w; }
;         __syncthreads();
.Lwcvt_ns2:
	ds_write2_b32 v43, v0, v1 offset1:1
	ds_write2_b32 v43, v2, v3 offset0:2 offset1:3
	ds_write2_b32 v44, v4, v5 offset1:1
	ds_write2_b32 v44, v6, v7 offset0:2 offset1:3
	ds_write2_b32 v45, v8, v9 offset1:1
	ds_write2_b32 v45, v10, v11 offset0:2 offset1:3
	ds_write2_b32 v46, v12, v13 offset1:1
	ds_write2_b32 v46, v14, v15 offset0:2 offset1:3
	ds_write2_b32 v47, v16, v17 offset1:1
	ds_write2_b32 v47, v18, v19 offset0:2 offset1:3
	ds_write2_b32 v48, v20, v21 offset1:1
	ds_write2_b32 v48, v22, v23 offset0:2 offset1:3
	ds_write2_b32 v49, v24, v25 offset1:1
	ds_write2_b32 v49, v26, v27 offset0:2 offset1:3
	ds_write2_b32 v50, v28, v29 offset1:1
	ds_write2_b32 v50, v30, v31 offset0:2 offset1:3
	v_add_u32_e32 v8, 0x400, v42
	s_waitcnt lgkmcnt(0)
	s_barrier
	v_add_u32_e32 v0, s12, v41
	ds_read2_b32 v[2:3], v42 offset1:65
	ds_read2_b32 v[4:5], v42 offset0:130 offset1:195
	ds_read2_b32 v[6:7], v8 offset0:4 offset1:69
	ds_read2_b32 v[8:9], v8 offset0:134 offset1:199
	s_sub_i32 s13, 0, s19
	v_ashrrev_i32_e32 v1, 31, v0
	s_add_i32 s14, s17, s13
	v_lshlrev_b64 v[0:1], 11, v[0:1]
	v_lshl_add_u64 v[0:1], s[6:7], 0, v[0:1]
	s_ashr_i32 s15, s14, 31
	v_lshl_add_u64 v[0:1], s[14:15], 1, v[0:1]
	v_mov_b32_e32 v35, v184
	v_lshl_add_u64 v[10:11], v[0:1], 0, v[34:35]
	s_waitcnt lgkmcnt(3)
	v_cvt_pk_bf16_f32 v0, v2, v3
	s_waitcnt lgkmcnt(2)
	v_cvt_pk_bf16_f32 v1, v4, v5
	s_waitcnt lgkmcnt(0)
	v_cvt_pk_bf16_f32 v3, v8, v9
	v_add_u32_e32 v4, 0x4000, v42
	v_add_u32_e32 v8, 0x4400, v42
	v_add_u32_e32 v12, 0x4600, v42
	v_cvt_pk_bf16_f32 v2, v6, v7
	ds_read2_b32 v[4:5], v4 offset0:64 offset1:129
	v_add_u32_e32 v6, 0x4200, v42
	ds_read2_b32 v[8:9], v8 offset0:68 offset1:133
	ds_read2_b32 v[12:13], v12 offset0:70 offset1:135
	ds_read2_b32 v[6:7], v6 offset0:66 offset1:131
	global_store_dwordx4 v[10:11], v[0:3], off
	s_add_i32 s16, s16, s25
	s_add_i32 s17, s17, s18
	s_waitcnt lgkmcnt(3)
	v_cvt_pk_bf16_f32 v0, v4, v5
	s_waitcnt lgkmcnt(2)
	v_cvt_pk_bf16_f32 v2, v8, v9
	s_waitcnt lgkmcnt(1)
	v_cvt_pk_bf16_f32 v3, v12, v13
	v_add_u32_e32 v4, 0x8000, v42
	v_add_u32_e32 v8, 0x8400, v42
	v_add_u32_e32 v12, 0x8800, v42
	s_waitcnt lgkmcnt(0)
	v_cvt_pk_bf16_f32 v1, v6, v7
	ds_read2_b32 v[4:5], v4 offset0:128 offset1:193
	ds_read2_b32 v[6:7], v8 offset0:2 offset1:67
	ds_read2_b32 v[8:9], v8 offset0:132 offset1:197
	ds_read2_b32 v[12:13], v12 offset0:6 offset1:71
	global_store_dwordx4 v[10:11], v[0:3], off offset:128
	s_cmpk_lt_i32 s16, 0x90
	s_waitcnt lgkmcnt(3)
	v_cvt_pk_bf16_f32 v0, v4, v5
	s_waitcnt lgkmcnt(2)
	v_cvt_pk_bf16_f32 v1, v6, v7
	s_waitcnt lgkmcnt(1)
	v_cvt_pk_bf16_f32 v2, v8, v9
	s_waitcnt lgkmcnt(0)
	v_cvt_pk_bf16_f32 v3, v12, v13
	v_add_u32_e32 v4, 0xc200, v42
	v_add_u32_e32 v6, 0xc400, v42
	v_add_u32_e32 v8, 0xc600, v42
	v_add_u32_e32 v12, 0xc800, v42
	ds_read2_b32 v[4:5], v4 offset0:64 offset1:129
	ds_read2_b32 v[6:7], v6 offset0:66 offset1:131
	ds_read2_b32 v[8:9], v8 offset0:68 offset1:133
	ds_read2_b32 v[12:13], v12 offset0:70 offset1:135
	global_store_dwordx4 v[10:11], v[0:3], off offset:256
	s_waitcnt lgkmcnt(3)
	s_nop 0
	v_cvt_pk_bf16_f32 v0, v4, v5
	s_waitcnt lgkmcnt(2)
	v_cvt_pk_bf16_f32 v1, v6, v7
	s_waitcnt lgkmcnt(1)
	v_cvt_pk_bf16_f32 v2, v8, v9
	s_waitcnt lgkmcnt(0)
	v_cvt_pk_bf16_f32 v3, v12, v13
	global_store_dwordx4 v[10:11], v[0:3], off offset:384
	s_barrier
	s_cbranch_scc0 .LBB0_785

; __device__ void transpose_job(const float* __restrict__ src, int K, int Nsrc, bf16_t* __restrict__ dst, int Ndst, int mode, LAS float* tile, int b0, int nb, const float* __restrict__ gain) {
;     ...
;         for (int rr = 0; rr < 8; ++rr) { v[rr] = make_float4(0.f, 0.f, 0.f, 0.f);
;             if (ns0 + c4 + 3 < Nsrc) v[rr] = *(const float4*)(src + (size_t)(k0 + r + rr * 32) * Nsrc + ns0 + c4);
;             if (gain) { const float gk = gain[k0 + r + rr * 32]; v[rr].x *= gk; v[rr].y *= gk; v[rr].z *= gk; v[rr].w *= gk; } }
.LBB0_755:
	s_or_b64 exec, exec, s[14:15]
	v_cndmask_b32_e64 v4, 0, 1, s[10:11]
	v_cmp_ne_u32_e64 s[42:43], 1, v4
	s_andn2_b64 vcc, exec, s[10:11]
	v_ashrrev_i32_e32 v37, 31, v36
	s_cbranch_vccnz .LBB0_757
	v_lshl_add_u64 v[76:77], v[36:37], 2, s[8:9]
	global_load_dword v60, v[76:77], off

; __device__ void transpose_job(const float* __restrict__ src, int K, int Nsrc, bf16_t* __restrict__ dst, int Ndst, int mode, LAS float* tile, int b0, int nb, const float* __restrict__ gain) {
;     ...
;         for (int rr = 0; rr < 8; ++rr) { v[rr] = make_float4(0.f, 0.f, 0.f, 0.f);
;             if (ns0 + c4 + 3 < Nsrc) v[rr] = *(const float4*)(src + (size_t)(k0 + r + rr * 32) * Nsrc + ns0 + c4);
;             if (gain) { const float gk = gain[k0 + r + rr * 32]; v[rr].x *= gk; v[rr].y *= gk; v[rr].z *= gk; v[rr].w *= gk; } }
.LBB0_759:
	s_or_b64 exec, exec, s[14:15]
	s_and_b64 vcc, exec, s[42:43]
	s_cbranch_vccnz .LBB0_761
	v_lshl_add_u64 v[76:77], v[36:37], 2, s[8:9]
	global_load_dword v62, v[76:77], off offset:128

; __device__ void transpose_job(const float* __restrict__ src, int K, int Nsrc, bf16_t* __restrict__ dst, int Ndst, int mode, LAS float* tile, int b0, int nb, const float* __restrict__ gain) {
;     ...
;         for (int rr = 0; rr < 8; ++rr) { v[rr] = make_float4(0.f, 0.f, 0.f, 0.f);
;             if (ns0 + c4 + 3 < Nsrc) v[rr] = *(const float4*)(src + (size_t)(k0 + r + rr * 32) * Nsrc + ns0 + c4);
;             if (gain) { const float gk = gain[k0 + r + rr * 32]; v[rr].x *= gk; v[rr].y *= gk; v[rr].z *= gk; v[rr].w *= gk; } }
.LBB0_763:
	s_or_b64 exec, exec, s[14:15]
	s_and_b64 vcc, exec, s[42:43]
	s_cbranch_vccnz .LBB0_765
	v_lshl_add_u64 v[76:77], v[36:37], 2, s[8:9]
	global_load_dword v64, v[76:77], off offset:256

; __device__ void transpose_job(const float* __restrict__ src, int K, int Nsrc, bf16_t* __restrict__ dst, int Ndst, int mode, LAS float* tile, int b0, int nb, const float* __restrict__ gain) {
;     ...
;         for (int rr = 0; rr < 8; ++rr) { v[rr] = make_float4(0.f, 0.f, 0.f, 0.f);
;             if (ns0 + c4 + 3 < Nsrc) v[rr] = *(const float4*)(src + (size_t)(k0 + r + rr * 32) * Nsrc + ns0 + c4);
;             if (gain) { const float gk = gain[k0 + r + rr * 32]; v[rr].x *= gk; v[rr].y *= gk; v[rr].z *= gk; v[rr].w *= gk; } }
.LBB0_767:
	s_or_b64 exec, exec, s[14:15]
	s_and_b64 vcc, exec, s[42:43]
	s_cbranch_vccnz .LBB0_769
	v_lshl_add_u64 v[76:77], v[36:37], 2, s[8:9]
	global_load_dword v66, v[76:77], off offset:384

; __device__ void transpose_job(const float* __restrict__ src, int K, int Nsrc, bf16_t* __restrict__ dst, int Ndst, int mode, LAS float* tile, int b0, int nb, const float* __restrict__ gain) {
;     ...
;         for (int rr = 0; rr < 8; ++rr) { v[rr] = make_float4(0.f, 0.f, 0.f, 0.f);
;             if (ns0 + c4 + 3 < Nsrc) v[rr] = *(const float4*)(src + (size_t)(k0 + r + rr * 32) * Nsrc + ns0 + c4);
;             if (gain) { const float gk = gain[k0 + r + rr * 32]; v[rr].x *= gk; v[rr].y *= gk; v[rr].z *= gk; v[rr].w *= gk; } }
.LBB0_771:
	s_or_b64 exec, exec, s[14:15]
	s_and_b64 vcc, exec, s[42:43]
	s_cbranch_vccnz .LBB0_773
	v_lshl_add_u64 v[76:77], v[36:37], 2, s[8:9]
	global_load_dword v68, v[76:77], off offset:512

; __device__ void transpose_job(const float* __restrict__ src, int K, int Nsrc, bf16_t* __restrict__ dst, int Ndst, int mode, LAS float* tile, int b0, int nb, const float* __restrict__ gain) {
;     ...
;         for (int rr = 0; rr < 8; ++rr) { v[rr] = make_float4(0.f, 0.f, 0.f, 0.f);
;             if (ns0 + c4 + 3 < Nsrc) v[rr] = *(const float4*)(src + (size_t)(k0 + r + rr * 32) * Nsrc + ns0 + c4);
;             if (gain) { const float gk = gain[k0 + r + rr * 32]; v[rr].x *= gk; v[rr].y *= gk; v[rr].z *= gk; v[rr].w *= gk; } }
.LBB0_775:
	s_or_b64 exec, exec, s[14:15]
	s_and_b64 vcc, exec, s[42:43]
	s_cbranch_vccnz .LBB0_777
	v_lshl_add_u64 v[76:77], v[36:37], 2, s[8:9]
	global_load_dword v70, v[76:77], off offset:640

; __device__ void transpose_job(const float* __restrict__ src, int K, int Nsrc, bf16_t* __restrict__ dst, int Ndst, int mode, LAS float* tile, int b0, int nb, const float* __restrict__ gain) {
;     ...
;         for (int rr = 0; rr < 8; ++rr) { v[rr] = make_float4(0.f, 0.f, 0.f, 0.f);
;             if (ns0 + c4 + 3 < Nsrc) v[rr] = *(const float4*)(src + (size_t)(k0 + r + rr * 32) * Nsrc + ns0 + c4);
;             if (gain) { const float gk = gain[k0 + r + rr * 32]; v[rr].x *= gk; v[rr].y *= gk; v[rr].z *= gk; v[rr].w *= gk; } }
.LBB0_779:
	s_or_b64 exec, exec, s[14:15]
	s_and_b64 vcc, exec, s[42:43]
	s_cbranch_vccnz .LBB0_781
	v_lshl_add_u64 v[76:77], v[36:37], 2, s[8:9]
	global_load_dword v72, v[76:77], off offset:768

; __device__ void transpose_job(const float* __restrict__ src, int K, int Nsrc, bf16_t* __restrict__ dst, int Ndst, int mode, LAS float* tile, int b0, int nb, const float* __restrict__ gain) {
;     ...
;         for (int rr = 0; rr < 8; ++rr) { v[rr] = make_float4(0.f, 0.f, 0.f, 0.f);
;             if (ns0 + c4 + 3 < Nsrc) v[rr] = *(const float4*)(src + (size_t)(k0 + r + rr * 32) * Nsrc + ns0 + c4);
;             if (gain) { const float gk = gain[k0 + r + rr * 32]; v[rr].x *= gk; v[rr].y *= gk; v[rr].z *= gk; v[rr].w *= gk; } }
.LBB0_783:
	s_or_b64 exec, exec, s[14:15]
	s_and_b64 vcc, exec, s[42:43]
	s_cbranch_vccnz .LBB0_752
	v_lshl_add_u64 v[76:77], v[36:37], 2, s[8:9]
	global_load_dword v74, v[76:77], off offset:896
	s_branch .LBB0_752

;     __device__ __forceinline__ void operator()(AccRef acc, const Unit& u, int wr, int wc, int fr, int fq, const LAS float* rsl) const {
;     ...
;             for (int m = 0; m < 4; ++m) { const int r = row0 + ai * 128 + m * 16; bf16_t* rowp = O + (size_t)r * ldc + col0; const float rs = rsl[ai * 128 + wr * 64 + m * 16 + fr];
;                 f32x4 c4 = (f32x4){1.f, 1.f, 1.f, 1.f}, s4 = (f32x4){0.f, 0.f, 0.f, 0.f};
;                 if (u.pn < 8) { const int pos = (rowbase + r) & 8191; c4 = *(const f32x4*)(cs + pos * 64 + f); s4 = *(const f32x4*)(sn + pos * 64 + f);
;                     if (u.pn >= 4) { c4 *= 0.08838834764831845f; s4 *= 0.08838834764831845f; } }
.Lretin_rot:
	s_cmp_eq_u32 s42, s16
	s_cselect_b32 s20, 0x300, 0
	s_cmp_lg_u32 s42, s13
	s_cselect_b32 s20, s20, 0x200
	s_cmp_lg_u32 s42, s12
	s_cselect_b32 s20, s20, 0x100
	v_lshl_add_u32 v165, s20, 2, v162
	ds_read_b32 v150, v165
	s_cmp_lt_i32 s44, 8
	s_cselect_b64 s[20:21], -1, 0
	s_cmp_gt_i32 s44, 3
	v_lshl_add_u32 v164, s42, 8, v151
	s_cselect_b64 s[42:43], -1, 0
	s_cmp_gt_i32 s44, 7
	v_mov_b32_e32 v148, 1.0
	v_mov_b32_e32 v146, 0
	v_mov_b32_e32 v152, 0
	v_mov_b32_e32 v153, 0
	v_mov_b32_e32 v154, 0
	v_mov_b32_e32 v155, 0
	v_mov_b32_e32 v156, 1.0
	v_mov_b32_e32 v157, 1.0
	v_mov_b32_e32 v158, 1.0
	v_mov_b32_e32 v159, 1.0
	s_movk_i32 s24, 0x3000
	s_mov_b32 s54, 0x3db504f3
	s_cbranch_scc1 .LBB0_997
	v_lshlrev_b32_e32 v144, 8, v164
	v_and_b32_e32 v144, 0x1fcf00, v144
	v_mov_b32_e32 v145, v184
	v_lshl_add_u64 v[152:153], v[136:137], 0, v[144:145]
	v_lshl_add_u64 v[144:145], v[138:139], 0, v[144:145]
	global_load_dwordx4 v[156:159], v[152:153], off
	global_load_dwordx4 v[152:155], v[144:145], off
	s_waitcnt vmcnt(1)
	v_pk_mul_f32 v[166:167], v[156:157], s[54:55] op_sel_hi:[1,0]
	v_pk_mul_f32 v[144:145], v[158:159], s[54:55] op_sel_hi:[1,0]
	v_cndmask_b32_e64 v156, v156, v166, s[42:43]
	v_cndmask_b32_e64 v157, v157, v167, s[42:43]
	v_cndmask_b32_e64 v158, v158, v144, s[42:43]
	v_cndmask_b32_e64 v159, v159, v145, s[42:43]
	s_waitcnt vmcnt(0)
	v_pk_mul_f32 v[168:169], v[154:155], s[54:55] op_sel_hi:[1,0]
	v_pk_mul_f32 v[170:171], v[152:153], s[54:55] op_sel_hi:[1,0]
	v_cndmask_b32_e64 v154, v154, v168, s[42:43]
	v_cndmask_b32_e64 v152, v152, v170, s[42:43]
	v_cndmask_b32_e64 v153, v153, v171, s[42:43]
	v_cndmask_b32_e64 v155, v155, v169, s[42:43]

; __device__ __forceinline__ unsigned pack2(float lo, float hi) { const f32x2_t v = {lo, hi}; const bf16x2_t b = __builtin_convertvector(v, bf16x2_t); return __builtin_bit_cast(unsigned, b); }
;     __device__ __forceinline__ void operator()(AccRef acc, const Unit& u, int wr, int wc, int fr, int fq, const LAS float* rsl) const {
;     ...
;             for (int m = 0; m < 4; ++m) { const int r = row0 + ai * 128 + m * 16; bf16_t* rowp = O + (size_t)r * ldc + col0; const float rs = rsl[ai * 128 + wr * 64 + m * 16 + fr];
;                 f32x4 c4 = (f32x4){1.f, 1.f, 1.f, 1.f}, s4 = (f32x4){0.f, 0.f, 0.f, 0.f};
;                 if (u.pn < 8) { const int pos = (rowbase + r) & 8191; c4 = *(const f32x4*)(cs + pos * 64 + f); s4 = *(const f32x4*)(sn + pos * 64 + f);
;                     if (u.pn >= 4) { c4 *= 0.08838834764831845f; s4 *= 0.08838834764831845f; } }
; #pragma unroll
;                 for (int bj = 0; bj < 2; ++bj) { const f32x4 t1 = rs * acc[ai][bj][m][0], t2 = rs * acc[ai][bj][m][1]; const f32x4 v0 = t1 * c4 - t2 * s4, v1 = t1 * s4 + t2 * c4;
;                     uint4 w; w.x = pack2(v0[0], v0[1]); w.y = pack2(v0[2], v0[3]); w.z = pack2(v1[0], v1[1]); w.w = pack2(v1[2], v1[3]);
;                     *(uint4*)(rowp + bj * 128) = w; } }
.LBB0_999:
	s_waitcnt lgkmcnt(0)
	v_pk_mul_f32 v[106:107], v[106:107], v[112:113] op_sel_hi:[1,0]
	v_pk_mul_f32 v[104:105], v[104:105], v[112:113] op_sel_hi:[1,0]
	v_mov_b64_e32 v[118:119], s[14:15]
	v_pk_mul_f32 v[110:111], v[110:111], v[112:113] op_sel_hi:[1,0]
	v_pk_mul_f32 v[108:109], v[108:109], v[112:113] op_sel_hi:[1,0]
	v_pk_mul_f32 v[120:121], v[104:105], v[146:147]
	v_pk_mul_f32 v[122:123], v[106:107], v[114:115]
	v_pk_mul_f32 v[104:105], v[104:105], v[148:149]
	v_pk_mul_f32 v[106:107], v[106:107], v[116:117]
	v_mad_i64_i32 v[118:119], s[20:21], v113, s24, v[118:119]
	v_pk_fma_f32 v[122:123], v[110:111], v[116:117], v[122:123] neg_lo:[0,0,1] neg_hi:[0,0,1]
	v_pk_fma_f32 v[120:121], v[108:109], v[148:149], v[120:121] neg_lo:[0,0,1] neg_hi:[0,0,1]
	v_pk_fma_f32 v[110:111], v[110:111], v[114:115], v[106:107]
	v_pk_fma_f32 v[106:107], v[108:109], v[146:147], v[104:105]
	v_lshl_add_u64 v[118:119], v[144:145], 1, v[118:119]
	v_cvt_pk_bf16_f32 v104, v120, v121
	v_cvt_pk_bf16_f32 v105, v122, v123
	v_cvt_pk_bf16_f32 v106, v106, v107
	v_cvt_pk_bf16_f32 v107, v110, v111
	v_pk_mul_f32 v[98:99], v[98:99], v[112:113] op_sel_hi:[1,0]
	v_pk_mul_f32 v[96:97], v[96:97], v[112:113] op_sel_hi:[1,0]
	global_store_dwordx4 v[118:119], v[104:107], off
	v_pk_mul_f32 v[102:103], v[102:103], v[112:113] op_sel_hi:[1,0]
	v_pk_mul_f32 v[100:101], v[100:101], v[112:113] op_sel_hi:[1,0]
	v_pk_mul_f32 v[104:105], v[96:97], v[146:147]
	v_pk_mul_f32 v[106:107], v[98:99], v[114:115]
	v_pk_mul_f32 v[96:97], v[96:97], v[148:149]
	v_pk_mul_f32 v[98:99], v[98:99], v[116:117]
	v_pk_fma_f32 v[106:107], v[102:103], v[116:117], v[106:107] neg_lo:[0,0,1] neg_hi:[0,0,1]
	v_pk_fma_f32 v[104:105], v[100:101], v[148:149], v[104:105] neg_lo:[0,0,1] neg_hi:[0,0,1]
	v_pk_fma_f32 v[102:103], v[102:103], v[114:115], v[98:99]
	v_pk_fma_f32 v[98:99], v[100:101], v[146:147], v[96:97]
	ds_read_b32 v100, v165 offset:128
	v_cvt_pk_bf16_f32 v96, v104, v105
	v_cvt_pk_bf16_f32 v97, v106, v107
	v_cvt_pk_bf16_f32 v98, v98, v99
	v_cvt_pk_bf16_f32 v99, v102, v103
	v_readlane_b32 s86, v254, 52
	global_store_dwordx4 v[118:119], v[96:99], off offset:256
	s_and_b64 vcc, exec, s[44:45]
	v_mov_b32_e32 v102, 0
	v_or_b32_e32 v97, 32, v164
	v_mov_b32_e32 v98, 1.0
	v_mov_b32_e32 v96, 0
	v_mov_b32_e32 v103, 0
	v_mov_b32_e32 v104, 0
	v_mov_b32_e32 v105, 0
	v_mov_b32_e32 v106, 1.0
	v_mov_b32_e32 v107, 1.0
	v_mov_b32_e32 v108, 1.0
	v_mov_b32_e32 v109, 1.0
	v_readlane_b32 s87, v254, 53
	v_mov_b32_e32 v249, v229
	v_mov_b32_e32 v248, v190
	v_mov_b32_e32 v250, v230
	s_cbranch_vccnz .LBB0_1001
	v_lshlrev_b32_e32 v99, 8, v97
	v_and_b32_e32 v102, 0x1fef00, v99
	v_mov_b32_e32 v103, v184
	v_lshl_add_u64 v[104:105], v[136:137], 0, v[102:103]
	v_lshl_add_u64 v[102:103], v[138:139], 0, v[102:103]
	global_load_dwordx4 v[106:109], v[104:105], off
	global_load_dwordx4 v[102:105], v[102:103], off
	s_waitcnt vmcnt(1)
	v_pk_mul_f32 v[110:111], v[108:109], s[54:55] op_sel_hi:[1,0]
	v_pk_mul_f32 v[112:113], v[106:107], s[54:55] op_sel_hi:[1,0]
	v_cndmask_b32_e64 v108, v108, v110, s[42:43]
	v_cndmask_b32_e64 v106, v106, v112, s[42:43]
	v_cndmask_b32_e64 v107, v107, v113, s[42:43]
	v_cndmask_b32_e64 v109, v109, v111, s[42:43]
	s_waitcnt vmcnt(0)
	v_pk_mul_f32 v[114:115], v[104:105], s[54:55] op_sel_hi:[1,0]
	v_pk_mul_f32 v[116:117], v[102:103], s[54:55] op_sel_hi:[1,0]
	v_cndmask_b32_e64 v104, v104, v114, s[42:43]
	v_cndmask_b32_e64 v102, v102, v116, s[42:43]
	v_cndmask_b32_e64 v103, v103, v117, s[42:43]
	v_cndmask_b32_e64 v105, v105, v115, s[42:43]

; __device__ __forceinline__ unsigned pack2(float lo, float hi) { const f32x2_t v = {lo, hi}; const bf16x2_t b = __builtin_convertvector(v, bf16x2_t); return __builtin_bit_cast(unsigned, b); }
;     __device__ __forceinline__ void operator()(AccRef acc, const Unit& u, int wr, int wc, int fr, int fq, const LAS float* rsl) const {
;     ...
;             for (int m = 0; m < 4; ++m) { const int r = row0 + ai * 128 + m * 16; bf16_t* rowp = O + (size_t)r * ldc + col0; const float rs = rsl[ai * 128 + wr * 64 + m * 16 + fr];
;                 f32x4 c4 = (f32x4){1.f, 1.f, 1.f, 1.f}, s4 = (f32x4){0.f, 0.f, 0.f, 0.f};
;                 if (u.pn < 8) { const int pos = (rowbase + r) & 8191; c4 = *(const f32x4*)(cs + pos * 64 + f); s4 = *(const f32x4*)(sn + pos * 64 + f);
;                     if (u.pn >= 4) { c4 *= 0.08838834764831845f; s4 *= 0.08838834764831845f; } }
; #pragma unroll
;                 for (int bj = 0; bj < 2; ++bj) { const f32x4 t1 = rs * acc[ai][bj][m][0], t2 = rs * acc[ai][bj][m][1]; const f32x4 v0 = t1 * c4 - t2 * s4, v1 = t1 * s4 + t2 * c4;
;                     uint4 w; w.x = pack2(v0[0], v0[1]); w.y = pack2(v0[2], v0[3]); w.z = pack2(v1[0], v1[1]); w.w = pack2(v1[2], v1[3]);
;                     *(uint4*)(rowp + bj * 128) = w; } }
.LBB0_1003:
	s_waitcnt lgkmcnt(0)
	v_pk_mul_f32 v[74:75], v[74:75], v[80:81] op_sel_hi:[1,0]
	v_pk_mul_f32 v[72:73], v[72:73], v[80:81] op_sel_hi:[1,0]
	v_mov_b64_e32 v[86:87], s[14:15]
	v_pk_mul_f32 v[78:79], v[78:79], v[80:81] op_sel_hi:[1,0]
	v_pk_mul_f32 v[76:77], v[76:77], v[80:81] op_sel_hi:[1,0]
	v_pk_mul_f32 v[88:89], v[72:73], v[96:97]
	v_pk_mul_f32 v[90:91], v[74:75], v[82:83]
	v_pk_mul_f32 v[72:73], v[72:73], v[98:99]
	v_pk_mul_f32 v[74:75], v[74:75], v[84:85]
	v_mad_i64_i32 v[86:87], s[20:21], v81, s24, v[86:87]
	v_pk_fma_f32 v[90:91], v[78:79], v[84:85], v[90:91] neg_lo:[0,0,1] neg_hi:[0,0,1]
	v_pk_fma_f32 v[88:89], v[76:77], v[98:99], v[88:89] neg_lo:[0,0,1] neg_hi:[0,0,1]
	v_pk_fma_f32 v[78:79], v[78:79], v[82:83], v[74:75]
	v_pk_fma_f32 v[74:75], v[76:77], v[96:97], v[72:73]
	v_lshl_add_u64 v[86:87], v[144:145], 1, v[86:87]
	v_cvt_pk_bf16_f32 v72, v88, v89
	v_cvt_pk_bf16_f32 v73, v90, v91
	v_cvt_pk_bf16_f32 v74, v74, v75
	v_cvt_pk_bf16_f32 v75, v78, v79
	v_pk_mul_f32 v[66:67], v[66:67], v[80:81] op_sel_hi:[1,0]
	v_pk_mul_f32 v[64:65], v[64:65], v[80:81] op_sel_hi:[1,0]
	global_store_dwordx4 v[86:87], v[72:75], off
	v_pk_mul_f32 v[70:71], v[70:71], v[80:81] op_sel_hi:[1,0]
	v_pk_mul_f32 v[68:69], v[68:69], v[80:81] op_sel_hi:[1,0]
	v_pk_mul_f32 v[72:73], v[64:65], v[96:97]
	v_pk_mul_f32 v[74:75], v[66:67], v[82:83]
	v_pk_mul_f32 v[64:65], v[64:65], v[98:99]
	v_pk_mul_f32 v[66:67], v[66:67], v[84:85]
	v_pk_fma_f32 v[74:75], v[70:71], v[84:85], v[74:75] neg_lo:[0,0,1] neg_hi:[0,0,1]
	v_pk_fma_f32 v[72:73], v[68:69], v[98:99], v[72:73] neg_lo:[0,0,1] neg_hi:[0,0,1]
	v_pk_fma_f32 v[70:71], v[70:71], v[82:83], v[66:67]
	v_pk_fma_f32 v[66:67], v[68:69], v[96:97], v[64:65]
	ds_read_b32 v68, v165 offset:512
	v_cvt_pk_bf16_f32 v64, v72, v73
	v_cvt_pk_bf16_f32 v65, v74, v75
	v_cvt_pk_bf16_f32 v66, v66, v67
	v_cvt_pk_bf16_f32 v67, v70, v71
	global_store_dwordx4 v[86:87], v[64:67], off offset:256
	s_and_b64 vcc, exec, s[44:45]
	v_mov_b32_e32 v70, 0
	v_add_u32_e32 v65, 0x80, v164
	v_mov_b32_e32 v66, 1.0
	v_mov_b32_e32 v64, 0
	v_mov_b32_e32 v71, 0
	v_mov_b32_e32 v72, 0
	v_mov_b32_e32 v73, 0
	v_mov_b32_e32 v74, 1.0
	v_mov_b32_e32 v75, 1.0
	v_mov_b32_e32 v76, 1.0
	v_mov_b32_e32 v77, 1.0
	s_cbranch_vccnz .LBB0_1005
	v_lshlrev_b32_e32 v67, 8, v65
	v_and_b32_e32 v70, 0x1fcf00, v67
	v_mov_b32_e32 v71, v184
	v_lshl_add_u64 v[72:73], v[136:137], 0, v[70:71]
	v_lshl_add_u64 v[70:71], v[138:139], 0, v[70:71]
	global_load_dwordx4 v[74:77], v[72:73], off
	global_load_dwordx4 v[70:73], v[70:71], off
	s_waitcnt vmcnt(1)
	v_pk_mul_f32 v[78:79], v[76:77], s[54:55] op_sel_hi:[1,0]
	v_pk_mul_f32 v[80:81], v[74:75], s[54:55] op_sel_hi:[1,0]
	v_cndmask_b32_e64 v76, v76, v78, s[42:43]
	v_cndmask_b32_e64 v74, v74, v80, s[42:43]
	v_cndmask_b32_e64 v75, v75, v81, s[42:43]
	v_cndmask_b32_e64 v77, v77, v79, s[42:43]
	s_waitcnt vmcnt(0)
	v_pk_mul_f32 v[82:83], v[72:73], s[54:55] op_sel_hi:[1,0]
	v_pk_mul_f32 v[84:85], v[70:71], s[54:55] op_sel_hi:[1,0]
	v_cndmask_b32_e64 v72, v72, v82, s[42:43]
	v_cndmask_b32_e64 v70, v70, v84, s[42:43]
	v_cndmask_b32_e64 v71, v71, v85, s[42:43]
	v_cndmask_b32_e64 v73, v73, v83, s[42:43]

; __device__ __forceinline__ unsigned pack2(float lo, float hi) { const f32x2_t v = {lo, hi}; const bf16x2_t b = __builtin_convertvector(v, bf16x2_t); return __builtin_bit_cast(unsigned, b); }
;     __device__ __forceinline__ void operator()(AccRef acc, const Unit& u, int wr, int wc, int fr, int fq, const LAS float* rsl) const {
;     ...
;             for (int m = 0; m < 4; ++m) { const int r = row0 + ai * 128 + m * 16; bf16_t* rowp = O + (size_t)r * ldc + col0; const float rs = rsl[ai * 128 + wr * 64 + m * 16 + fr];
;                 f32x4 c4 = (f32x4){1.f, 1.f, 1.f, 1.f}, s4 = (f32x4){0.f, 0.f, 0.f, 0.f};
;                 if (u.pn < 8) { const int pos = (rowbase + r) & 8191; c4 = *(const f32x4*)(cs + pos * 64 + f); s4 = *(const f32x4*)(sn + pos * 64 + f);
;                     if (u.pn >= 4) { c4 *= 0.08838834764831845f; s4 *= 0.08838834764831845f; } }
; #pragma unroll
;                 for (int bj = 0; bj < 2; ++bj) { const f32x4 t1 = rs * acc[ai][bj][m][0], t2 = rs * acc[ai][bj][m][1]; const f32x4 v0 = t1 * c4 - t2 * s4, v1 = t1 * s4 + t2 * c4;
;                     uint4 w; w.x = pack2(v0[0], v0[1]); w.y = pack2(v0[2], v0[3]); w.z = pack2(v1[0], v1[1]); w.w = pack2(v1[2], v1[3]);
;                     *(uint4*)(rowp + bj * 128) = w; } }
.LBB0_1007:
	s_waitcnt lgkmcnt(0)
	v_pk_mul_f32 v[42:43], v[42:43], v[48:49] op_sel_hi:[1,0]
	v_pk_mul_f32 v[40:41], v[40:41], v[48:49] op_sel_hi:[1,0]
	v_mov_b64_e32 v[54:55], s[14:15]
	v_pk_mul_f32 v[46:47], v[46:47], v[48:49] op_sel_hi:[1,0]
	v_pk_mul_f32 v[44:45], v[44:45], v[48:49] op_sel_hi:[1,0]
	v_pk_mul_f32 v[56:57], v[40:41], v[64:65]
	v_pk_mul_f32 v[58:59], v[42:43], v[50:51]
	v_pk_mul_f32 v[40:41], v[40:41], v[66:67]
	v_pk_mul_f32 v[42:43], v[42:43], v[52:53]
	v_mad_i64_i32 v[54:55], s[20:21], v49, s24, v[54:55]
	v_pk_fma_f32 v[58:59], v[46:47], v[52:53], v[58:59] neg_lo:[0,0,1] neg_hi:[0,0,1]
	v_pk_fma_f32 v[56:57], v[44:45], v[66:67], v[56:57] neg_lo:[0,0,1] neg_hi:[0,0,1]
	v_pk_fma_f32 v[46:47], v[46:47], v[50:51], v[42:43]
	v_pk_fma_f32 v[42:43], v[44:45], v[64:65], v[40:41]
	v_lshl_add_u64 v[54:55], v[144:145], 1, v[54:55]
	v_cvt_pk_bf16_f32 v40, v56, v57
	v_cvt_pk_bf16_f32 v41, v58, v59
	v_cvt_pk_bf16_f32 v42, v42, v43
	v_cvt_pk_bf16_f32 v43, v46, v47
	v_pk_mul_f32 v[34:35], v[34:35], v[48:49] op_sel_hi:[1,0]
	v_pk_mul_f32 v[32:33], v[32:33], v[48:49] op_sel_hi:[1,0]
	global_store_dwordx4 v[54:55], v[40:43], off
	v_pk_mul_f32 v[38:39], v[38:39], v[48:49] op_sel_hi:[1,0]
	v_pk_mul_f32 v[36:37], v[36:37], v[48:49] op_sel_hi:[1,0]
	v_pk_mul_f32 v[40:41], v[32:33], v[64:65]
	v_pk_mul_f32 v[42:43], v[34:35], v[50:51]
	v_pk_mul_f32 v[32:33], v[32:33], v[66:67]
	v_pk_mul_f32 v[34:35], v[34:35], v[52:53]
	v_pk_fma_f32 v[42:43], v[38:39], v[52:53], v[42:43] neg_lo:[0,0,1] neg_hi:[0,0,1]
	v_pk_fma_f32 v[40:41], v[36:37], v[66:67], v[40:41] neg_lo:[0,0,1] neg_hi:[0,0,1]
	v_pk_fma_f32 v[38:39], v[38:39], v[50:51], v[34:35]
	v_pk_fma_f32 v[34:35], v[36:37], v[64:65], v[32:33]
	ds_read_b32 v36, v165 offset:640
	v_cvt_pk_bf16_f32 v32, v40, v41
	v_cvt_pk_bf16_f32 v33, v42, v43
	v_cvt_pk_bf16_f32 v34, v34, v35
	v_cvt_pk_bf16_f32 v35, v38, v39
	global_store_dwordx4 v[54:55], v[32:35], off offset:256
	s_and_b64 vcc, exec, s[44:45]
	v_mov_b32_e32 v38, 0
	v_add_u32_e32 v33, 0xa0, v164
	v_mov_b32_e32 v34, 1.0
	v_mov_b32_e32 v32, 0
	v_mov_b32_e32 v39, 0
	v_mov_b32_e32 v40, 0
	v_mov_b32_e32 v41, 0
	v_mov_b32_e32 v42, 1.0
	v_mov_b32_e32 v43, 1.0
	v_mov_b32_e32 v44, 1.0
	v_mov_b32_e32 v45, 1.0
	s_cbranch_vccnz .LBB0_1009
	v_lshlrev_b32_e32 v35, 8, v33
	v_and_b32_e32 v38, 0x1fef00, v35
	v_mov_b32_e32 v39, v184
	v_lshl_add_u64 v[40:41], v[136:137], 0, v[38:39]
	v_lshl_add_u64 v[38:39], v[138:139], 0, v[38:39]
	global_load_dwordx4 v[42:45], v[40:41], off
	global_load_dwordx4 v[38:41], v[38:39], off
	s_waitcnt vmcnt(1)
	v_pk_mul_f32 v[46:47], v[44:45], s[54:55] op_sel_hi:[1,0]
	v_pk_mul_f32 v[48:49], v[42:43], s[54:55] op_sel_hi:[1,0]
	v_cndmask_b32_e64 v44, v44, v46, s[42:43]
	v_cndmask_b32_e64 v42, v42, v48, s[42:43]
	v_cndmask_b32_e64 v43, v43, v49, s[42:43]
	v_cndmask_b32_e64 v45, v45, v47, s[42:43]
	s_waitcnt vmcnt(0)
	v_pk_mul_f32 v[50:51], v[40:41], s[54:55] op_sel_hi:[1,0]
	v_pk_mul_f32 v[52:53], v[38:39], s[54:55] op_sel_hi:[1,0]
	v_cndmask_b32_e64 v40, v40, v50, s[42:43]
	v_cndmask_b32_e64 v38, v38, v52, s[42:43]
	v_cndmask_b32_e64 v39, v39, v53, s[42:43]
	v_cndmask_b32_e64 v41, v41, v51, s[42:43]
